# stack18 + GEMM K-loops: back edge rotated (7.11) - loop-carried pointer arithmetic executed before the last barrier of the iteration, back edge lands on the first ds_read
# baseline (speedup 1.0000x reference)
; #define PG8_STAGE(bufoff, gbase, voff) do { _Pragma("unroll") for (int _i = 0; _i < 2; ++_i) \
;         __builtin_amdgcn_global_load_lds((const unsigned*)((const char*)(gbase) + (voff)[_i]), (PG8_LAS unsigned*)(lds + (bufoff) + ldsw + _i * 8192), 16, 0, 0); } while (0)
; #define PG8_LDA(dst, b, h) do { _Pragma("unroll") for (int m = 0; m < 4; ++m) _Pragma("unroll") for (int k = 0; k < 2; ++k) dst[m][k] = *(const PG8_LAS bf16x8*)(lds + PG8_SA(b, h) + aoff + m * 2048 + k * 1024); } while (0)
; #define PG8_LDB(dst, b, h) do { _Pragma("unroll") for (int n = 0; n < 2; ++n) _Pragma("unroll") for (int k = 0; k < 2; ++k) dst[n][k] = *(const PG8_LAS bf16x8*)(lds + PG8_SB(b, h) + boff + n * 2048 + k * 1024); } while (0)
; #define PG8_MMA(ai, bj, At, Bt) do { __builtin_amdgcn_s_setprio(1); _Pragma("unroll") for (int m = 0; m < 4; ++m) _Pragma("unroll") for (int n = 0; n < 2; ++n) _Pragma("unroll") for (int k = 0; k < 2; ++k) \
;         acc[ai][bj][m][n] = __builtin_amdgcn_mfma_f32_16x16x32_bf16(Bt[n][k], At[m][k], acc[ai][bj][m][n], 0, 0, 0); __builtin_amdgcn_s_setprio(0); } while (0)
; #define PG8_WAIT_V(n) asm volatile("s_waitcnt vmcnt(" #n ")" ::: "memory")
; #define PG8_WAIT_L(n) asm volatile("s_waitcnt lgkmcnt(" #n ")" ::: "memory")
; #define PG8_BAR __builtin_amdgcn_s_barrier()
; #define PG8_SCHED __builtin_amdgcn_sched_barrier(0)
; template <class Epi, class Sched, bool ALIGN_EPI = false, bool SP2 = false>
; __device__ __forceinline__ void gemm_phase(PG8_LAS unsigned char* lds, const Gemm g, const Sched& S, const Epi& E, int wid_in) {
;     ...
;             PG8_LDB(B0, 0, 0); PG8_LDB(B1, 0, 1); PG8_SCHED; PG8_LDA(At, 0, 0); PG8_STAGE(PG8_SA(1, 1), a1 + hstep, voffA);
;             PG8_WAIT_V(8); PG8_WAIT_L(0); PG8_BAR; PG8_MMA(0, 0, At, B0); PG8_MMA(0, 1, At, B1); PG8_BAR; PG8_SCHED;
;             PG8_LDA(At, 0, 1); PG8_STAGE(PG8_SB(0, 0), b2, voffB); PG8_STAGE(PG8_SB(0, 1), b2 + hstep, voffB); PG8_STAGE(PG8_SA(0, 0), a2, voffA);
;             PG8_WAIT_V(8); PG8_WAIT_L(0); PG8_BAR; PG8_MMA(1, 0, At, B0); PG8_MMA(1, 1, At, B1); PG8_BAR; PG8_SCHED;
.Lrot_0:
	ds_read_b128 v[142:145], v154
	ds_read_b128 v[146:149], v154 offset:1024
	ds_read_b128 v[150:153], v154 offset:2048
	ds_read_b128 v[154:157], v154 offset:3072
	ds_read_b128 v[158:161], v170
	ds_read_b128 v[162:165], v170 offset:1024
	ds_read_b128 v[166:169], v170 offset:2048
	ds_read_b128 v[170:173], v170 offset:3072
	v_lshl_add_u64 v[220:221], s[26:27], 0, v[138:139]
	s_add_i32 m0, s13, 0xc000
	ds_read_b128 v[174:177], v141
	ds_read_b128 v[178:181], v141 offset:1024
	ds_read_b128 v[182:185], v141 offset:2048
	ds_read_b128 v[186:189], v141 offset:3072
	ds_read_b128 v[190:193], v141 offset:4096
	ds_read_b128 v[208:211], v141 offset:5120
	ds_read_b128 v[212:215], v141 offset:6144
	ds_read_b128 v[216:219], v141 offset:7168
	global_load_lds_dwordx4 v[220:221], off
	v_lshl_add_u64 v[220:221], s[26:27], 0, v[136:137]
	s_add_i32 m0, s13, 0xe000
	s_nop 0
	global_load_lds_dwordx4 v[220:221], off
	s_waitcnt vmcnt(8)
	s_waitcnt lgkmcnt(0)
	s_barrier
	s_waitcnt lgkmcnt(0)
	v_mfma_f32_16x16x32_bf16 v[126:129], v[142:145], v[174:177], v[126:129]
	v_mfma_f32_16x16x32_bf16 v[122:125], v[150:153], v[174:177], v[122:125]
	v_mfma_f32_16x16x32_bf16 v[118:121], v[142:145], v[182:185], v[118:121]
	v_mfma_f32_16x16x32_bf16 v[114:117], v[150:153], v[182:185], v[114:117]
	v_mfma_f32_16x16x32_bf16 v[102:105], v[142:145], v[190:193], v[102:105]
	v_mfma_f32_16x16x32_bf16 v[98:101], v[150:153], v[190:193], v[98:101]
	v_mfma_f32_16x16x32_bf16 v[86:89], v[142:145], v[212:215], v[86:89]
	v_mfma_f32_16x16x32_bf16 v[82:85], v[150:153], v[212:215], v[82:85]
	v_mfma_f32_16x16x32_bf16 v[126:129], v[146:149], v[178:181], v[126:129]
	v_mfma_f32_16x16x32_bf16 v[122:125], v[154:157], v[178:181], v[122:125]
	v_mfma_f32_16x16x32_bf16 v[118:121], v[146:149], v[186:189], v[118:121]
	v_mfma_f32_16x16x32_bf16 v[114:117], v[154:157], v[186:189], v[114:117]
	v_mfma_f32_16x16x32_bf16 v[102:105], v[146:149], v[208:211], v[102:105]
	v_mfma_f32_16x16x32_bf16 v[98:101], v[154:157], v[208:211], v[98:101]
	v_mfma_f32_16x16x32_bf16 v[86:89], v[146:149], v[216:219], v[86:89]
	v_mfma_f32_16x16x32_bf16 v[82:85], v[154:157], v[216:219], v[82:85]
	v_mfma_f32_16x16x32_bf16 v[110:113], v[158:161], v[174:177], v[110:113]
	v_mfma_f32_16x16x32_bf16 v[106:109], v[166:169], v[174:177], v[106:109]
	v_mfma_f32_16x16x32_bf16 v[94:97], v[158:161], v[182:185], v[94:97]
	v_mfma_f32_16x16x32_bf16 v[90:93], v[166:169], v[182:185], v[90:93]
	v_mfma_f32_16x16x32_bf16 v[78:81], v[158:161], v[190:193], v[78:81]
	v_mfma_f32_16x16x32_bf16 v[74:77], v[166:169], v[190:193], v[74:77]
	v_mfma_f32_16x16x32_bf16 v[70:73], v[158:161], v[212:215], v[70:73]
	v_mfma_f32_16x16x32_bf16 v[66:69], v[166:169], v[212:215], v[66:69]
	v_mfma_f32_16x16x32_bf16 v[110:113], v[162:165], v[178:181], v[110:113]
	v_mfma_f32_16x16x32_bf16 v[106:109], v[170:173], v[178:181], v[106:109]
	v_mfma_f32_16x16x32_bf16 v[94:97], v[162:165], v[186:189], v[94:97]
	v_mfma_f32_16x16x32_bf16 v[90:93], v[170:173], v[186:189], v[90:93]
	v_mfma_f32_16x16x32_bf16 v[78:81], v[162:165], v[208:211], v[78:81]
	v_mfma_f32_16x16x32_bf16 v[74:77], v[170:173], v[208:211], v[74:77]
	v_mfma_f32_16x16x32_bf16 v[70:73], v[162:165], v[216:219], v[70:73]
	v_mfma_f32_16x16x32_bf16 v[66:69], v[170:173], v[216:219], v[66:69]
	s_barrier
	s_add_i32 s40, s40, s59
	v_lshl_add_u64 v[220:221], s[28:29], 0, v[0:1]
	s_mov_b32 m0, s40
	ds_read_b128 v[174:177], v141 offset:16384
	ds_read_b128 v[178:181], v141 offset:17408
	ds_read_b128 v[182:185], v141 offset:18432
	ds_read_b128 v[186:189], v141 offset:19456
	ds_read_b128 v[190:193], v141 offset:20480
	ds_read_b128 v[208:211], v141 offset:21504
	ds_read_b128 v[212:215], v141 offset:22528
	ds_read_b128 v[216:219], v141 offset:23552
	global_load_lds_dwordx4 v[220:221], off
	s_add_i32 m0, s40, 0x2000
	s_add_u32 s72, s28, 0x80000
	v_lshl_add_u64 v[222:223], s[28:29], 0, v[134:135]
	s_addc_u32 s73, s29, 0
	s_add_i32 s40, s41, s59
	global_load_lds_dwordx4 v[222:223], off
	v_lshl_add_u64 v[224:225], s[72:73], 0, v[0:1]
	s_mov_b32 m0, s40
	v_lshl_add_u64 v[226:227], s[30:31], 0, v[132:133]
	global_load_lds_dwordx4 v[224:225], off
	v_lshl_add_u64 v[224:225], s[72:73], 0, v[134:135]
	s_add_i32 m0, s40, 0x2000
	s_nop 0
	global_load_lds_dwordx4 v[224:225], off
	v_lshl_add_u64 v[224:225], s[30:31], 0, v[130:131]
	s_mov_b32 m0, s13
	s_nop 0
	global_load_lds_dwordx4 v[224:225], off
	s_mov_b32 m0, s36
	s_nop 0
	global_load_lds_dwordx4 v[226:227], off
	s_waitcnt vmcnt(8)
	s_waitcnt lgkmcnt(0)
	s_barrier
	s_waitcnt lgkmcnt(0)
	v_mfma_f32_16x16x32_bf16 v[62:65], v[142:145], v[174:177], v[62:65]
	v_mfma_f32_16x16x32_bf16 v[58:61], v[150:153], v[174:177], v[58:61]
	v_mfma_f32_16x16x32_bf16 v[54:57], v[142:145], v[182:185], v[54:57]
	v_mfma_f32_16x16x32_bf16 v[50:53], v[150:153], v[182:185], v[50:53]
	v_mfma_f32_16x16x32_bf16 v[38:41], v[142:145], v[190:193], v[38:41]
	v_mfma_f32_16x16x32_bf16 v[34:37], v[150:153], v[190:193], v[34:37]
	v_mfma_f32_16x16x32_bf16 v[22:25], v[142:145], v[212:215], v[22:25]
	v_mfma_f32_16x16x32_bf16 v[18:21], v[150:153], v[212:215], v[18:21]
	v_mfma_f32_16x16x32_bf16 v[62:65], v[146:149], v[178:181], v[62:65]
	v_mfma_f32_16x16x32_bf16 v[58:61], v[154:157], v[178:181], v[58:61]
	v_mfma_f32_16x16x32_bf16 v[54:57], v[146:149], v[186:189], v[54:57]
	v_mfma_f32_16x16x32_bf16 v[50:53], v[154:157], v[186:189], v[50:53]
	v_mfma_f32_16x16x32_bf16 v[38:41], v[146:149], v[208:211], v[38:41]
	v_mfma_f32_16x16x32_bf16 v[34:37], v[154:157], v[208:211], v[34:37]
	v_mfma_f32_16x16x32_bf16 v[22:25], v[146:149], v[216:219], v[22:25]
	v_mfma_f32_16x16x32_bf16 v[18:21], v[154:157], v[216:219], v[18:21]
	v_mfma_f32_16x16x32_bf16 v[46:49], v[158:161], v[174:177], v[46:49]
	v_mfma_f32_16x16x32_bf16 v[42:45], v[166:169], v[174:177], v[42:45]
	v_mfma_f32_16x16x32_bf16 v[30:33], v[158:161], v[182:185], v[30:33]
	v_mfma_f32_16x16x32_bf16 v[26:29], v[166:169], v[182:185], v[26:29]
	v_mfma_f32_16x16x32_bf16 v[14:17], v[158:161], v[190:193], v[14:17]
	v_mfma_f32_16x16x32_bf16 v[10:13], v[166:169], v[190:193], v[10:13]
	v_mfma_f32_16x16x32_bf16 v[6:9], v[158:161], v[212:215], v[6:9]
	v_mfma_f32_16x16x32_bf16 v[2:5], v[166:169], v[212:215], v[2:5]
	v_mfma_f32_16x16x32_bf16 v[46:49], v[162:165], v[178:181], v[46:49]
	v_mfma_f32_16x16x32_bf16 v[42:45], v[170:173], v[178:181], v[42:45]
	v_mfma_f32_16x16x32_bf16 v[30:33], v[162:165], v[186:189], v[30:33]
	v_mfma_f32_16x16x32_bf16 v[26:29], v[170:173], v[186:189], v[26:29]
	v_mfma_f32_16x16x32_bf16 v[14:17], v[162:165], v[208:211], v[14:17]
	v_mfma_f32_16x16x32_bf16 v[10:13], v[170:173], v[208:211], v[10:13]
	v_mfma_f32_16x16x32_bf16 v[6:9], v[162:165], v[216:219], v[6:9]
	v_mfma_f32_16x16x32_bf16 v[2:5], v[170:173], v[216:219], v[2:5]
	s_barrier
; #define PG8_STAGE(bufoff, gbase, voff) do { _Pragma("unroll") for (int _i = 0; _i < 2; ++_i) \
;         __builtin_amdgcn_global_load_lds((const unsigned*)((const char*)(gbase) + (voff)[_i]), (PG8_LAS unsigned*)(lds + (bufoff) + ldsw + _i * 8192), 16, 0, 0); } while (0)
; #define PG8_LDA(dst, b, h) do { _Pragma("unroll") for (int m = 0; m < 4; ++m) _Pragma("unroll") for (int k = 0; k < 2; ++k) dst[m][k] = *(const PG8_LAS bf16x8*)(lds + PG8_SA(b, h) + aoff + m * 2048 + k * 1024); } while (0)
; #define PG8_LDB(dst, b, h) do { _Pragma("unroll") for (int n = 0; n < 2; ++n) _Pragma("unroll") for (int k = 0; k < 2; ++k) dst[n][k] = *(const PG8_LAS bf16x8*)(lds + PG8_SB(b, h) + boff + n * 2048 + k * 1024); } while (0)
; #define PG8_MMA(ai, bj, At, Bt) do { __builtin_amdgcn_s_setprio(1); _Pragma("unroll") for (int m = 0; m < 4; ++m) _Pragma("unroll") for (int n = 0; n < 2; ++n) _Pragma("unroll") for (int k = 0; k < 2; ++k) \
;         acc[ai][bj][m][n] = __builtin_amdgcn_mfma_f32_16x16x32_bf16(Bt[n][k], At[m][k], acc[ai][bj][m][n], 0, 0, 0); __builtin_amdgcn_s_setprio(0); } while (0)
; #define PG8_WAIT_V(n) asm volatile("s_waitcnt vmcnt(" #n ")" ::: "memory")
; #define PG8_WAIT_L(n) asm volatile("s_waitcnt lgkmcnt(" #n ")" ::: "memory")
; #define PG8_BAR __builtin_amdgcn_s_barrier()
; #define PG8_SCHED __builtin_amdgcn_sched_barrier(0)
; template <class Epi, class Sched, bool ALIGN_EPI = false, bool SP2 = false>
; __device__ __forceinline__ void gemm_phase(PG8_LAS unsigned char* lds, const Gemm g, const Sched& S, const Epi& E, int wid_in) {
;     ...
;             PG8_LDB(B0, 1, 0); PG8_LDB(B1, 1, 1); PG8_SCHED; PG8_LDA(At, 1, 0); PG8_STAGE(PG8_SA(0, 1), a2 + hstep, voffA);
;             PG8_WAIT_V(8); PG8_WAIT_L(0); PG8_BAR; PG8_MMA(0, 0, At, B0); PG8_MMA(0, 1, At, B1); PG8_BAR; PG8_SCHED;
	s_add_i32 s40, 0, 0x18000
	s_add_i32 s41, 0, 0x1c000
	v_add_u32_e32 v154, s40, v140
	v_add_u32_e32 v170, s41, v140
	ds_read_b128 v[142:145], v154
	ds_read_b128 v[146:149], v154 offset:1024
	ds_read_b128 v[150:153], v154 offset:2048
	ds_read_b128 v[154:157], v154 offset:3072
	ds_read_b128 v[158:161], v170
	ds_read_b128 v[162:165], v170 offset:1024
	ds_read_b128 v[166:169], v170 offset:2048
	ds_read_b128 v[170:173], v170 offset:3072
	s_add_u32 s30, s30, 0x80000
	s_addc_u32 s31, s31, 0
	s_mov_b32 m0, s37
	v_lshl_add_u64 v[228:229], s[30:31], 0, v[130:131]
	ds_read_b128 v[174:177], v141 offset:32768
	ds_read_b128 v[178:181], v141 offset:33792
	ds_read_b128 v[182:185], v141 offset:34816
	ds_read_b128 v[186:189], v141 offset:35840
	ds_read_b128 v[190:193], v141 offset:36864
	ds_read_b128 v[208:211], v141 offset:37888
	ds_read_b128 v[212:215], v141 offset:38912
	ds_read_b128 v[216:219], v141 offset:39936
	global_load_lds_dwordx4 v[228:229], off
	v_lshl_add_u64 v[228:229], s[30:31], 0, v[132:133]
	s_mov_b32 m0, s38
	s_nop 0
	global_load_lds_dwordx4 v[228:229], off
	s_waitcnt vmcnt(8)
	s_waitcnt lgkmcnt(0)
	s_barrier
	s_waitcnt lgkmcnt(0)
	v_mfma_f32_16x16x32_bf16 v[126:129], v[142:145], v[174:177], v[126:129]
	v_mfma_f32_16x16x32_bf16 v[122:125], v[150:153], v[174:177], v[122:125]
	v_mfma_f32_16x16x32_bf16 v[118:121], v[142:145], v[182:185], v[118:121]
	v_mfma_f32_16x16x32_bf16 v[114:117], v[150:153], v[182:185], v[114:117]
	v_mfma_f32_16x16x32_bf16 v[102:105], v[142:145], v[190:193], v[102:105]
	v_mfma_f32_16x16x32_bf16 v[98:101], v[150:153], v[190:193], v[98:101]
	v_mfma_f32_16x16x32_bf16 v[86:89], v[142:145], v[212:215], v[86:89]
	v_mfma_f32_16x16x32_bf16 v[82:85], v[150:153], v[212:215], v[82:85]
	v_mfma_f32_16x16x32_bf16 v[126:129], v[146:149], v[178:181], v[126:129]
	v_mfma_f32_16x16x32_bf16 v[122:125], v[154:157], v[178:181], v[122:125]
	v_mfma_f32_16x16x32_bf16 v[118:121], v[146:149], v[186:189], v[118:121]
	v_mfma_f32_16x16x32_bf16 v[114:117], v[154:157], v[186:189], v[114:117]
	v_mfma_f32_16x16x32_bf16 v[102:105], v[146:149], v[208:211], v[102:105]
	v_mfma_f32_16x16x32_bf16 v[98:101], v[154:157], v[208:211], v[98:101]
	v_mfma_f32_16x16x32_bf16 v[86:89], v[146:149], v[216:219], v[86:89]
	v_mfma_f32_16x16x32_bf16 v[82:85], v[154:157], v[216:219], v[82:85]
	v_mfma_f32_16x16x32_bf16 v[110:113], v[158:161], v[174:177], v[110:113]
	v_mfma_f32_16x16x32_bf16 v[106:109], v[166:169], v[174:177], v[106:109]
	v_mfma_f32_16x16x32_bf16 v[94:97], v[158:161], v[182:185], v[94:97]
	v_mfma_f32_16x16x32_bf16 v[90:93], v[166:169], v[182:185], v[90:93]
	v_mfma_f32_16x16x32_bf16 v[78:81], v[158:161], v[190:193], v[78:81]
	v_mfma_f32_16x16x32_bf16 v[74:77], v[166:169], v[190:193], v[74:77]
	v_mfma_f32_16x16x32_bf16 v[70:73], v[158:161], v[212:215], v[70:73]
	v_mfma_f32_16x16x32_bf16 v[66:69], v[166:169], v[212:215], v[66:69]
	v_mfma_f32_16x16x32_bf16 v[110:113], v[162:165], v[178:181], v[110:113]
	v_mfma_f32_16x16x32_bf16 v[106:109], v[170:173], v[178:181], v[106:109]
	v_mfma_f32_16x16x32_bf16 v[94:97], v[162:165], v[186:189], v[94:97]
	v_mfma_f32_16x16x32_bf16 v[90:93], v[170:173], v[186:189], v[90:93]
	v_mfma_f32_16x16x32_bf16 v[78:81], v[162:165], v[208:211], v[78:81]
	v_mfma_f32_16x16x32_bf16 v[74:77], v[170:173], v[208:211], v[74:77]
	v_mfma_f32_16x16x32_bf16 v[70:73], v[162:165], v[216:219], v[70:73]
	v_mfma_f32_16x16x32_bf16 v[66:69], v[170:173], v[216:219], v[66:69]
	s_barrier
; #define PG8_STAGE(bufoff, gbase, voff) do { _Pragma("unroll") for (int _i = 0; _i < 2; ++_i) \
;         __builtin_amdgcn_global_load_lds((const unsigned*)((const char*)(gbase) + (voff)[_i]), (PG8_LAS unsigned*)(lds + (bufoff) + ldsw + _i * 8192), 16, 0, 0); } while (0)
; #define PG8_LDA(dst, b, h) do { _Pragma("unroll") for (int m = 0; m < 4; ++m) _Pragma("unroll") for (int k = 0; k < 2; ++k) dst[m][k] = *(const PG8_LAS bf16x8*)(lds + PG8_SA(b, h) + aoff + m * 2048 + k * 1024); } while (0)
; #define PG8_MMA(ai, bj, At, Bt) do { __builtin_amdgcn_s_setprio(1); _Pragma("unroll") for (int m = 0; m < 4; ++m) _Pragma("unroll") for (int n = 0; n < 2; ++n) _Pragma("unroll") for (int k = 0; k < 2; ++k) \
;         acc[ai][bj][m][n] = __builtin_amdgcn_mfma_f32_16x16x32_bf16(Bt[n][k], At[m][k], acc[ai][bj][m][n], 0, 0, 0); __builtin_amdgcn_s_setprio(0); } while (0)
; #define PG8_WAIT_V(n) asm volatile("s_waitcnt vmcnt(" #n ")" ::: "memory")
; #define PG8_WAIT_L(n) asm volatile("s_waitcnt lgkmcnt(" #n ")" ::: "memory")
; #define PG8_BAR __builtin_amdgcn_s_barrier()
; #define PG8_SCHED __builtin_amdgcn_sched_barrier(0)
; template <class Epi, class Sched, bool ALIGN_EPI = false, bool SP2 = false>
; __device__ __forceinline__ void gemm_phase(PG8_LAS unsigned char* lds, const Gemm g, const Sched& S, const Epi& E, int wid_in) {
;     ...
;         for (int t = 0; t < nt; t += 2) {
;             const bool last = (t == nt - 2);
;             const char* a1 = cA + (size_t)(t + 1) * kstep;
;             const char* a2 = last ? nA : cA + (size_t)(t + 2) * kstep; const char* b2 = last ? nB : cB + (size_t)(t + 2) * kstep;
;             const char* a3 = a2 + kstep; const char* b3 = b2 + kstep;
;             if (last && has_next) S.a_ready(nxt);
;     ...
;             PG8_LDA(At, 1, 1); PG8_STAGE(PG8_SB(1, 0), b3, voffB); PG8_STAGE(PG8_SB(1, 1), b3 + hstep, voffB); PG8_STAGE(PG8_SA(1, 0), a3, voffA);
;             PG8_WAIT_V(8); PG8_WAIT_L(0); PG8_BAR; PG8_MMA(1, 0, At, B0); PG8_MMA(1, 1, At, B1); PG8_BAR; PG8_SCHED;
	s_add_i32 s30, s40, s59
	v_lshl_add_u64 v[220:221], v[220:221], 0, s[94:95]
	s_mov_b32 m0, s30
	ds_read_b128 v[174:177], v141 offset:49152
	ds_read_b128 v[178:181], v141 offset:50176
	ds_read_b128 v[182:185], v141 offset:51200
	ds_read_b128 v[186:189], v141 offset:52224
	ds_read_b128 v[190:193], v141 offset:53248
	ds_read_b128 v[208:211], v141 offset:54272
	ds_read_b128 v[212:215], v141 offset:55296
	ds_read_b128 v[216:219], v141 offset:56320
	global_load_lds_dwordx4 v[220:221], off
	s_add_i32 m0, s30, 0x2000
	s_add_u32 s28, s28, 0x80080
	v_lshl_add_u64 v[220:221], v[222:223], 0, s[94:95]
	s_addc_u32 s29, s29, 0
	s_add_i32 s30, s41, s59
	global_load_lds_dwordx4 v[220:221], off
	v_lshl_add_u64 v[220:221], s[28:29], 0, v[0:1]
	s_mov_b32 m0, s30
	s_nop 0
	global_load_lds_dwordx4 v[220:221], off
	v_lshl_add_u64 v[220:221], s[28:29], 0, v[134:135]
	s_add_i32 m0, s30, 0x2000
	s_nop 0
	global_load_lds_dwordx4 v[220:221], off
	v_lshl_add_u64 v[220:221], v[224:225], 0, s[94:95]
	s_mov_b32 m0, s52
	s_nop 0
	global_load_lds_dwordx4 v[220:221], off
	v_lshl_add_u64 v[220:221], v[226:227], 0, s[94:95]
	s_mov_b32 m0, s53
	s_nop 0
	global_load_lds_dwordx4 v[220:221], off
	s_waitcnt vmcnt(8)
	s_waitcnt lgkmcnt(0)
	s_barrier
	s_waitcnt lgkmcnt(0)
	v_mfma_f32_16x16x32_bf16 v[62:65], v[142:145], v[174:177], v[62:65]
	v_mfma_f32_16x16x32_bf16 v[58:61], v[150:153], v[174:177], v[58:61]
	v_mfma_f32_16x16x32_bf16 v[54:57], v[142:145], v[182:185], v[54:57]
	v_mfma_f32_16x16x32_bf16 v[50:53], v[150:153], v[182:185], v[50:53]
	v_mfma_f32_16x16x32_bf16 v[38:41], v[142:145], v[190:193], v[38:41]
	v_mfma_f32_16x16x32_bf16 v[34:37], v[150:153], v[190:193], v[34:37]
	v_mfma_f32_16x16x32_bf16 v[22:25], v[142:145], v[212:215], v[22:25]
	v_mfma_f32_16x16x32_bf16 v[18:21], v[150:153], v[212:215], v[18:21]
	v_mfma_f32_16x16x32_bf16 v[62:65], v[146:149], v[178:181], v[62:65]
	v_mfma_f32_16x16x32_bf16 v[58:61], v[154:157], v[178:181], v[58:61]
	v_mfma_f32_16x16x32_bf16 v[54:57], v[146:149], v[186:189], v[54:57]
	v_mfma_f32_16x16x32_bf16 v[50:53], v[154:157], v[186:189], v[50:53]
	v_mfma_f32_16x16x32_bf16 v[38:41], v[146:149], v[208:211], v[38:41]
	v_mfma_f32_16x16x32_bf16 v[34:37], v[154:157], v[208:211], v[34:37]
	v_mfma_f32_16x16x32_bf16 v[22:25], v[146:149], v[216:219], v[22:25]
	v_mfma_f32_16x16x32_bf16 v[18:21], v[154:157], v[216:219], v[18:21]
	v_mfma_f32_16x16x32_bf16 v[46:49], v[158:161], v[174:177], v[46:49]
	v_mfma_f32_16x16x32_bf16 v[42:45], v[166:169], v[174:177], v[42:45]
	v_mfma_f32_16x16x32_bf16 v[30:33], v[158:161], v[182:185], v[30:33]
	v_mfma_f32_16x16x32_bf16 v[26:29], v[166:169], v[182:185], v[26:29]
	v_mfma_f32_16x16x32_bf16 v[14:17], v[158:161], v[190:193], v[14:17]
	v_mfma_f32_16x16x32_bf16 v[10:13], v[166:169], v[190:193], v[10:13]
	v_mfma_f32_16x16x32_bf16 v[6:9], v[158:161], v[212:215], v[6:9]
	v_mfma_f32_16x16x32_bf16 v[2:5], v[166:169], v[212:215], v[2:5]
	v_mfma_f32_16x16x32_bf16 v[46:49], v[162:165], v[178:181], v[46:49]
	v_mfma_f32_16x16x32_bf16 v[42:45], v[170:173], v[178:181], v[42:45]
	v_mfma_f32_16x16x32_bf16 v[30:33], v[162:165], v[186:189], v[30:33]
	v_mfma_f32_16x16x32_bf16 v[26:29], v[170:173], v[186:189], v[26:29]
	v_mfma_f32_16x16x32_bf16 v[14:17], v[162:165], v[208:211], v[14:17]
	v_mfma_f32_16x16x32_bf16 v[10:13], v[170:173], v[208:211], v[10:13]
	v_mfma_f32_16x16x32_bf16 v[6:9], v[162:165], v[216:219], v[6:9]
	v_mfma_f32_16x16x32_bf16 v[2:5], v[170:173], v[216:219], v[2:5]
	s_add_i32 s63, s63, 2
	s_add_u32 s64, s64, 0x100
	s_addc_u32 s65, s65, 0
	s_add_u32 s26, s26, 0x100
	s_addc_u32 s27, s27, 0
	s_cmp_gt_u32 s63, 29
	s_cbranch_scc1 .Lrot_exit_0
	s_add_u32 s28, s26, 0xfff80080
	s_addc_u32 s29, s27, -1
	s_add_i32 s40, 0, 0x10000
	s_cmp_eq_u32 s63, 28
	s_cselect_b32 s31, s11, s29
	s_cselect_b32 s30, s19, s28
	s_cselect_b32 s29, s17, s65
	s_cselect_b32 s28, s62, s64
	s_add_i32 s41, 0, 0x14000
	v_add_u32_e32 v154, s40, v140
	v_add_u32_e32 v170, s41, v140
	s_barrier
	s_branch .Lrot_0
.Lrot_exit_0:
	s_barrier
	s_setprio 0
	s_and_b64 vcc, exec, s[14:15]
	s_cbranch_vccz .LBB0_281
	s_barrier

; #define PG8_STAGE(bufoff, gbase, voff) do { _Pragma("unroll") for (int _i = 0; _i < 2; ++_i) \
;         __builtin_amdgcn_global_load_lds((const unsigned*)((const char*)(gbase) + (voff)[_i]), (PG8_LAS unsigned*)(lds + (bufoff) + ldsw + _i * 8192), 16, 0, 0); } while (0)
; #define PG8_LDA(dst, b, h) do { _Pragma("unroll") for (int m = 0; m < 4; ++m) _Pragma("unroll") for (int k = 0; k < 2; ++k) dst[m][k] = *(const PG8_LAS bf16x8*)(lds + PG8_SA(b, h) + aoff + m * 2048 + k * 1024); } while (0)
; #define PG8_LDB(dst, b, h) do { _Pragma("unroll") for (int n = 0; n < 2; ++n) _Pragma("unroll") for (int k = 0; k < 2; ++k) dst[n][k] = *(const PG8_LAS bf16x8*)(lds + PG8_SB(b, h) + boff + n * 2048 + k * 1024); } while (0)
; #define PG8_MMA(ai, bj, At, Bt) do { __builtin_amdgcn_s_setprio(1); _Pragma("unroll") for (int m = 0; m < 4; ++m) _Pragma("unroll") for (int n = 0; n < 2; ++n) _Pragma("unroll") for (int k = 0; k < 2; ++k) \
;         acc[ai][bj][m][n] = __builtin_amdgcn_mfma_f32_16x16x32_bf16(Bt[n][k], At[m][k], acc[ai][bj][m][n], 0, 0, 0); __builtin_amdgcn_s_setprio(0); } while (0)
; #define PG8_WAIT_V(n) asm volatile("s_waitcnt vmcnt(" #n ")" ::: "memory")
; #define PG8_WAIT_L(n) asm volatile("s_waitcnt lgkmcnt(" #n ")" ::: "memory")
; #define PG8_BAR __builtin_amdgcn_s_barrier()
; #define PG8_SCHED __builtin_amdgcn_sched_barrier(0)
; template <class Epi, class Sched, bool ALIGN_EPI = false, bool SP2 = false>
; __device__ __forceinline__ void gemm_phase(PG8_LAS unsigned char* lds, const Gemm g, const Sched& S, const Epi& E, int wid_in) {
;     ...
;             PG8_LDB(B0, 0, 0); PG8_LDB(B1, 0, 1); PG8_SCHED; PG8_LDA(At, 0, 0); PG8_STAGE(PG8_SA(1, 1), a1 + hstep, voffA);
;             PG8_WAIT_V(8); PG8_WAIT_L(0); PG8_BAR; PG8_MMA(0, 0, At, B0); PG8_MMA(0, 1, At, B1); PG8_BAR; PG8_SCHED;
;             PG8_LDA(At, 0, 1); PG8_STAGE(PG8_SB(0, 0), b2, voffB); PG8_STAGE(PG8_SB(0, 1), b2 + hstep, voffB); PG8_STAGE(PG8_SA(0, 0), a2, voffA);
;             PG8_WAIT_V(8); PG8_WAIT_L(0); PG8_BAR; PG8_MMA(1, 0, At, B0); PG8_MMA(1, 1, At, B1); PG8_BAR; PG8_SCHED;
.Lrot_1:
	ds_read_b128 v[130:133], v142
	ds_read_b128 v[134:137], v142 offset:1024
	ds_read_b128 v[138:141], v142 offset:2048
	ds_read_b128 v[142:145], v142 offset:3072
	ds_read_b128 v[146:149], v158
	ds_read_b128 v[150:153], v158 offset:1024
	ds_read_b128 v[154:157], v158 offset:2048
	ds_read_b128 v[158:161], v158 offset:3072
	v_lshl_add_u64 v[220:221], s[30:31], 0, v[170:171]
	s_add_i32 m0, s29, 0xc000
	ds_read_b128 v[172:175], v189
	ds_read_b128 v[176:179], v189 offset:1024
	ds_read_b128 v[180:183], v189 offset:2048
	ds_read_b128 v[184:187], v189 offset:3072
	ds_read_b128 v[190:193], v189 offset:4096
	ds_read_b128 v[208:211], v189 offset:5120
	ds_read_b128 v[212:215], v189 offset:6144
	ds_read_b128 v[216:219], v189 offset:7168
	global_load_lds_dwordx4 v[220:221], off
	v_lshl_add_u64 v[220:221], s[30:31], 0, v[168:169]
	s_add_i32 m0, s29, 0xe000
	s_nop 0
	global_load_lds_dwordx4 v[220:221], off
	s_waitcnt vmcnt(8)
	s_waitcnt lgkmcnt(0)
	s_barrier
	s_waitcnt lgkmcnt(0)
	v_mfma_f32_16x16x32_bf16 v[126:129], v[130:133], v[172:175], v[126:129]
	v_mfma_f32_16x16x32_bf16 v[122:125], v[138:141], v[172:175], v[122:125]
	v_mfma_f32_16x16x32_bf16 v[118:121], v[130:133], v[180:183], v[118:121]
	v_mfma_f32_16x16x32_bf16 v[114:117], v[138:141], v[180:183], v[114:117]
	v_mfma_f32_16x16x32_bf16 v[102:105], v[130:133], v[190:193], v[102:105]
	v_mfma_f32_16x16x32_bf16 v[98:101], v[138:141], v[190:193], v[98:101]
	v_mfma_f32_16x16x32_bf16 v[86:89], v[130:133], v[212:215], v[86:89]
	v_mfma_f32_16x16x32_bf16 v[82:85], v[138:141], v[212:215], v[82:85]
	v_mfma_f32_16x16x32_bf16 v[126:129], v[134:137], v[176:179], v[126:129]
	v_mfma_f32_16x16x32_bf16 v[122:125], v[142:145], v[176:179], v[122:125]
	v_mfma_f32_16x16x32_bf16 v[118:121], v[134:137], v[184:187], v[118:121]
	v_mfma_f32_16x16x32_bf16 v[114:117], v[142:145], v[184:187], v[114:117]
	v_mfma_f32_16x16x32_bf16 v[102:105], v[134:137], v[208:211], v[102:105]
	v_mfma_f32_16x16x32_bf16 v[98:101], v[142:145], v[208:211], v[98:101]
	v_mfma_f32_16x16x32_bf16 v[86:89], v[134:137], v[216:219], v[86:89]
	v_mfma_f32_16x16x32_bf16 v[82:85], v[142:145], v[216:219], v[82:85]
	v_mfma_f32_16x16x32_bf16 v[110:113], v[146:149], v[172:175], v[110:113]
	v_mfma_f32_16x16x32_bf16 v[106:109], v[154:157], v[172:175], v[106:109]
	v_mfma_f32_16x16x32_bf16 v[94:97], v[146:149], v[180:183], v[94:97]
	v_mfma_f32_16x16x32_bf16 v[90:93], v[154:157], v[180:183], v[90:93]
	v_mfma_f32_16x16x32_bf16 v[78:81], v[146:149], v[190:193], v[78:81]
	v_mfma_f32_16x16x32_bf16 v[74:77], v[154:157], v[190:193], v[74:77]
	v_mfma_f32_16x16x32_bf16 v[70:73], v[146:149], v[212:215], v[70:73]
	v_mfma_f32_16x16x32_bf16 v[66:69], v[154:157], v[212:215], v[66:69]
	v_mfma_f32_16x16x32_bf16 v[110:113], v[150:153], v[176:179], v[110:113]
	v_mfma_f32_16x16x32_bf16 v[106:109], v[158:161], v[176:179], v[106:109]
	v_mfma_f32_16x16x32_bf16 v[94:97], v[150:153], v[184:187], v[94:97]
	v_mfma_f32_16x16x32_bf16 v[90:93], v[158:161], v[184:187], v[90:93]
	v_mfma_f32_16x16x32_bf16 v[78:81], v[150:153], v[208:211], v[78:81]
	v_mfma_f32_16x16x32_bf16 v[74:77], v[158:161], v[208:211], v[74:77]
	v_mfma_f32_16x16x32_bf16 v[70:73], v[150:153], v[216:219], v[70:73]
	v_mfma_f32_16x16x32_bf16 v[66:69], v[158:161], v[216:219], v[66:69]
	s_barrier
	s_add_i32 s40, s40, s59
	v_lshl_add_u64 v[220:221], s[34:35], 0, v[0:1]
	s_mov_b32 m0, s40
	ds_read_b128 v[172:175], v189 offset:16384
	ds_read_b128 v[176:179], v189 offset:17408
	ds_read_b128 v[180:183], v189 offset:18432
	ds_read_b128 v[184:187], v189 offset:19456
	ds_read_b128 v[190:193], v189 offset:20480
	ds_read_b128 v[208:211], v189 offset:21504
	ds_read_b128 v[212:215], v189 offset:22528
	ds_read_b128 v[216:219], v189 offset:23552
	global_load_lds_dwordx4 v[220:221], off
	s_add_i32 m0, s40, 0x2000
	s_add_u32 s40, s34, 0x40000
	v_lshl_add_u64 v[222:223], s[34:35], 0, v[166:167]
	s_addc_u32 s41, s35, 0
	s_add_i32 s42, s42, s59
	global_load_lds_dwordx4 v[222:223], off
	v_lshl_add_u64 v[224:225], s[40:41], 0, v[0:1]
	s_mov_b32 m0, s42
	v_lshl_add_u64 v[226:227], s[36:37], 0, v[164:165]
	global_load_lds_dwordx4 v[224:225], off
	v_lshl_add_u64 v[224:225], s[40:41], 0, v[166:167]
	s_add_i32 m0, s42, 0x2000
	s_nop 0
	global_load_lds_dwordx4 v[224:225], off
	v_lshl_add_u64 v[224:225], s[36:37], 0, v[162:163]
	s_mov_b32 m0, s29
	s_nop 0
	global_load_lds_dwordx4 v[224:225], off
	s_mov_b32 m0, s64
	s_nop 0
	global_load_lds_dwordx4 v[226:227], off
	s_waitcnt vmcnt(8)
	s_waitcnt lgkmcnt(0)
	s_barrier
	s_waitcnt lgkmcnt(0)
	v_mfma_f32_16x16x32_bf16 v[62:65], v[130:133], v[172:175], v[62:65]
	v_mfma_f32_16x16x32_bf16 v[58:61], v[138:141], v[172:175], v[58:61]
	v_mfma_f32_16x16x32_bf16 v[54:57], v[130:133], v[180:183], v[54:57]
	v_mfma_f32_16x16x32_bf16 v[50:53], v[138:141], v[180:183], v[50:53]
	v_mfma_f32_16x16x32_bf16 v[38:41], v[130:133], v[190:193], v[38:41]
	v_mfma_f32_16x16x32_bf16 v[34:37], v[138:141], v[190:193], v[34:37]
	v_mfma_f32_16x16x32_bf16 v[22:25], v[130:133], v[212:215], v[22:25]
	v_mfma_f32_16x16x32_bf16 v[18:21], v[138:141], v[212:215], v[18:21]
	v_mfma_f32_16x16x32_bf16 v[62:65], v[134:137], v[176:179], v[62:65]
	v_mfma_f32_16x16x32_bf16 v[58:61], v[142:145], v[176:179], v[58:61]
	v_mfma_f32_16x16x32_bf16 v[54:57], v[134:137], v[184:187], v[54:57]
	v_mfma_f32_16x16x32_bf16 v[50:53], v[142:145], v[184:187], v[50:53]
	v_mfma_f32_16x16x32_bf16 v[38:41], v[134:137], v[208:211], v[38:41]
	v_mfma_f32_16x16x32_bf16 v[34:37], v[142:145], v[208:211], v[34:37]
	v_mfma_f32_16x16x32_bf16 v[22:25], v[134:137], v[216:219], v[22:25]
	v_mfma_f32_16x16x32_bf16 v[18:21], v[142:145], v[216:219], v[18:21]
	v_mfma_f32_16x16x32_bf16 v[46:49], v[146:149], v[172:175], v[46:49]
	v_mfma_f32_16x16x32_bf16 v[42:45], v[154:157], v[172:175], v[42:45]
	v_mfma_f32_16x16x32_bf16 v[30:33], v[146:149], v[180:183], v[30:33]
	v_mfma_f32_16x16x32_bf16 v[26:29], v[154:157], v[180:183], v[26:29]
	v_mfma_f32_16x16x32_bf16 v[14:17], v[146:149], v[190:193], v[14:17]
	v_mfma_f32_16x16x32_bf16 v[10:13], v[154:157], v[190:193], v[10:13]
	v_mfma_f32_16x16x32_bf16 v[6:9], v[146:149], v[212:215], v[6:9]
	v_mfma_f32_16x16x32_bf16 v[2:5], v[154:157], v[212:215], v[2:5]
	v_mfma_f32_16x16x32_bf16 v[46:49], v[150:153], v[176:179], v[46:49]
	v_mfma_f32_16x16x32_bf16 v[42:45], v[158:161], v[176:179], v[42:45]
	v_mfma_f32_16x16x32_bf16 v[30:33], v[150:153], v[184:187], v[30:33]
	v_mfma_f32_16x16x32_bf16 v[26:29], v[158:161], v[184:187], v[26:29]
	v_mfma_f32_16x16x32_bf16 v[14:17], v[150:153], v[208:211], v[14:17]
	v_mfma_f32_16x16x32_bf16 v[10:13], v[158:161], v[208:211], v[10:13]
	v_mfma_f32_16x16x32_bf16 v[6:9], v[150:153], v[216:219], v[6:9]
	v_mfma_f32_16x16x32_bf16 v[2:5], v[158:161], v[216:219], v[2:5]
	s_barrier
; #define PG8_STAGE(bufoff, gbase, voff) do { _Pragma("unroll") for (int _i = 0; _i < 2; ++_i) \
;         __builtin_amdgcn_global_load_lds((const unsigned*)((const char*)(gbase) + (voff)[_i]), (PG8_LAS unsigned*)(lds + (bufoff) + ldsw + _i * 8192), 16, 0, 0); } while (0)
; #define PG8_LDA(dst, b, h) do { _Pragma("unroll") for (int m = 0; m < 4; ++m) _Pragma("unroll") for (int k = 0; k < 2; ++k) dst[m][k] = *(const PG8_LAS bf16x8*)(lds + PG8_SA(b, h) + aoff + m * 2048 + k * 1024); } while (0)
; #define PG8_LDB(dst, b, h) do { _Pragma("unroll") for (int n = 0; n < 2; ++n) _Pragma("unroll") for (int k = 0; k < 2; ++k) dst[n][k] = *(const PG8_LAS bf16x8*)(lds + PG8_SB(b, h) + boff + n * 2048 + k * 1024); } while (0)
; #define PG8_MMA(ai, bj, At, Bt) do { __builtin_amdgcn_s_setprio(1); _Pragma("unroll") for (int m = 0; m < 4; ++m) _Pragma("unroll") for (int n = 0; n < 2; ++n) _Pragma("unroll") for (int k = 0; k < 2; ++k) \
;         acc[ai][bj][m][n] = __builtin_amdgcn_mfma_f32_16x16x32_bf16(Bt[n][k], At[m][k], acc[ai][bj][m][n], 0, 0, 0); __builtin_amdgcn_s_setprio(0); } while (0)
; #define PG8_WAIT_V(n) asm volatile("s_waitcnt vmcnt(" #n ")" ::: "memory")
; #define PG8_WAIT_L(n) asm volatile("s_waitcnt lgkmcnt(" #n ")" ::: "memory")
; #define PG8_BAR __builtin_amdgcn_s_barrier()
; #define PG8_SCHED __builtin_amdgcn_sched_barrier(0)
; template <class Epi, class Sched, bool ALIGN_EPI = false, bool SP2 = false>
; __device__ __forceinline__ void gemm_phase(PG8_LAS unsigned char* lds, const Gemm g, const Sched& S, const Epi& E, int wid_in) {
;     ...
;             PG8_LDB(B0, 1, 0); PG8_LDB(B1, 1, 1); PG8_SCHED; PG8_LDA(At, 1, 0); PG8_STAGE(PG8_SA(0, 1), a2 + hstep, voffA);
;             PG8_WAIT_V(8); PG8_WAIT_L(0); PG8_BAR; PG8_MMA(0, 0, At, B0); PG8_MMA(0, 1, At, B1); PG8_BAR; PG8_SCHED;
	s_add_i32 s40, 0, 0x18000
	s_add_i32 s41, 0, 0x1c000
	v_add_u32_e32 v142, s40, v188
	v_add_u32_e32 v158, s41, v188
	ds_read_b128 v[130:133], v142
	ds_read_b128 v[134:137], v142 offset:1024
	ds_read_b128 v[138:141], v142 offset:2048
	ds_read_b128 v[142:145], v142 offset:3072
	ds_read_b128 v[146:149], v158
	ds_read_b128 v[150:153], v158 offset:1024
	ds_read_b128 v[154:157], v158 offset:2048
	ds_read_b128 v[158:161], v158 offset:3072
	s_add_u32 s36, s36, 0x40000
	s_addc_u32 s37, s37, 0
	s_mov_b32 m0, s65
	v_lshl_add_u64 v[228:229], s[36:37], 0, v[162:163]
	ds_read_b128 v[172:175], v189 offset:32768
	ds_read_b128 v[176:179], v189 offset:33792
	ds_read_b128 v[180:183], v189 offset:34816
	ds_read_b128 v[184:187], v189 offset:35840
	ds_read_b128 v[190:193], v189 offset:36864
	ds_read_b128 v[208:211], v189 offset:37888
	ds_read_b128 v[212:215], v189 offset:38912
	ds_read_b128 v[216:219], v189 offset:39936
	global_load_lds_dwordx4 v[228:229], off
	v_lshl_add_u64 v[228:229], s[36:37], 0, v[164:165]
	s_mov_b32 m0, s62
	s_nop 0
	global_load_lds_dwordx4 v[228:229], off
	s_waitcnt vmcnt(8)
	s_waitcnt lgkmcnt(0)
	s_barrier
	s_waitcnt lgkmcnt(0)
	v_mfma_f32_16x16x32_bf16 v[126:129], v[130:133], v[172:175], v[126:129]
	v_mfma_f32_16x16x32_bf16 v[122:125], v[138:141], v[172:175], v[122:125]
	v_mfma_f32_16x16x32_bf16 v[118:121], v[130:133], v[180:183], v[118:121]
	v_mfma_f32_16x16x32_bf16 v[114:117], v[138:141], v[180:183], v[114:117]
	v_mfma_f32_16x16x32_bf16 v[102:105], v[130:133], v[190:193], v[102:105]
	v_mfma_f32_16x16x32_bf16 v[98:101], v[138:141], v[190:193], v[98:101]
	v_mfma_f32_16x16x32_bf16 v[86:89], v[130:133], v[212:215], v[86:89]
	v_mfma_f32_16x16x32_bf16 v[82:85], v[138:141], v[212:215], v[82:85]
	v_mfma_f32_16x16x32_bf16 v[126:129], v[134:137], v[176:179], v[126:129]
	v_mfma_f32_16x16x32_bf16 v[122:125], v[142:145], v[176:179], v[122:125]
	v_mfma_f32_16x16x32_bf16 v[118:121], v[134:137], v[184:187], v[118:121]
	v_mfma_f32_16x16x32_bf16 v[114:117], v[142:145], v[184:187], v[114:117]
	v_mfma_f32_16x16x32_bf16 v[102:105], v[134:137], v[208:211], v[102:105]
	v_mfma_f32_16x16x32_bf16 v[98:101], v[142:145], v[208:211], v[98:101]
	v_mfma_f32_16x16x32_bf16 v[86:89], v[134:137], v[216:219], v[86:89]
	v_mfma_f32_16x16x32_bf16 v[82:85], v[142:145], v[216:219], v[82:85]
	v_mfma_f32_16x16x32_bf16 v[110:113], v[146:149], v[172:175], v[110:113]
	v_mfma_f32_16x16x32_bf16 v[106:109], v[154:157], v[172:175], v[106:109]
	v_mfma_f32_16x16x32_bf16 v[94:97], v[146:149], v[180:183], v[94:97]
	v_mfma_f32_16x16x32_bf16 v[90:93], v[154:157], v[180:183], v[90:93]
	v_mfma_f32_16x16x32_bf16 v[78:81], v[146:149], v[190:193], v[78:81]
	v_mfma_f32_16x16x32_bf16 v[74:77], v[154:157], v[190:193], v[74:77]
	v_mfma_f32_16x16x32_bf16 v[70:73], v[146:149], v[212:215], v[70:73]
	v_mfma_f32_16x16x32_bf16 v[66:69], v[154:157], v[212:215], v[66:69]
	v_mfma_f32_16x16x32_bf16 v[110:113], v[150:153], v[176:179], v[110:113]
	v_mfma_f32_16x16x32_bf16 v[106:109], v[158:161], v[176:179], v[106:109]
	v_mfma_f32_16x16x32_bf16 v[94:97], v[150:153], v[184:187], v[94:97]
	v_mfma_f32_16x16x32_bf16 v[90:93], v[158:161], v[184:187], v[90:93]
	v_mfma_f32_16x16x32_bf16 v[78:81], v[150:153], v[208:211], v[78:81]
	v_mfma_f32_16x16x32_bf16 v[74:77], v[158:161], v[208:211], v[74:77]
	v_mfma_f32_16x16x32_bf16 v[70:73], v[150:153], v[216:219], v[70:73]
	v_mfma_f32_16x16x32_bf16 v[66:69], v[158:161], v[216:219], v[66:69]
	s_barrier
; #define PG8_STAGE(bufoff, gbase, voff) do { _Pragma("unroll") for (int _i = 0; _i < 2; ++_i) \
;         __builtin_amdgcn_global_load_lds((const unsigned*)((const char*)(gbase) + (voff)[_i]), (PG8_LAS unsigned*)(lds + (bufoff) + ldsw + _i * 8192), 16, 0, 0); } while (0)
; #define PG8_LDA(dst, b, h) do { _Pragma("unroll") for (int m = 0; m < 4; ++m) _Pragma("unroll") for (int k = 0; k < 2; ++k) dst[m][k] = *(const PG8_LAS bf16x8*)(lds + PG8_SA(b, h) + aoff + m * 2048 + k * 1024); } while (0)
; #define PG8_MMA(ai, bj, At, Bt) do { __builtin_amdgcn_s_setprio(1); _Pragma("unroll") for (int m = 0; m < 4; ++m) _Pragma("unroll") for (int n = 0; n < 2; ++n) _Pragma("unroll") for (int k = 0; k < 2; ++k) \
;         acc[ai][bj][m][n] = __builtin_amdgcn_mfma_f32_16x16x32_bf16(Bt[n][k], At[m][k], acc[ai][bj][m][n], 0, 0, 0); __builtin_amdgcn_s_setprio(0); } while (0)
; #define PG8_WAIT_V(n) asm volatile("s_waitcnt vmcnt(" #n ")" ::: "memory")
; #define PG8_WAIT_L(n) asm volatile("s_waitcnt lgkmcnt(" #n ")" ::: "memory")
; #define PG8_BAR __builtin_amdgcn_s_barrier()
; #define PG8_SCHED __builtin_amdgcn_sched_barrier(0)
; template <class Epi, class Sched, bool ALIGN_EPI = false, bool SP2 = false>
; __device__ __forceinline__ void gemm_phase(PG8_LAS unsigned char* lds, const Gemm g, const Sched& S, const Epi& E, int wid_in) {
;     ...
;         for (int t = 0; t < nt; t += 2) {
;             const bool last = (t == nt - 2);
;             const char* a1 = cA + (size_t)(t + 1) * kstep;
;             const char* a2 = last ? nA : cA + (size_t)(t + 2) * kstep; const char* b2 = last ? nB : cB + (size_t)(t + 2) * kstep;
;             const char* a3 = a2 + kstep; const char* b3 = b2 + kstep;
;             if (last && has_next) S.a_ready(nxt);
;     ...
;             PG8_LDA(At, 1, 1); PG8_STAGE(PG8_SB(1, 0), b3, voffB); PG8_STAGE(PG8_SB(1, 1), b3 + hstep, voffB); PG8_STAGE(PG8_SA(1, 0), a3, voffA);
;             PG8_WAIT_V(8); PG8_WAIT_L(0); PG8_BAR; PG8_MMA(1, 0, At, B0); PG8_MMA(1, 1, At, B1); PG8_BAR; PG8_SCHED;
	s_add_i32 s36, s40, s59
	v_lshl_add_u64 v[220:221], v[220:221], 0, s[94:95]
	s_mov_b32 m0, s36
	ds_read_b128 v[172:175], v189 offset:49152
	ds_read_b128 v[176:179], v189 offset:50176
	ds_read_b128 v[180:183], v189 offset:51200
	ds_read_b128 v[184:187], v189 offset:52224
	ds_read_b128 v[190:193], v189 offset:53248
	ds_read_b128 v[208:211], v189 offset:54272
	ds_read_b128 v[212:215], v189 offset:55296
	ds_read_b128 v[216:219], v189 offset:56320
	global_load_lds_dwordx4 v[220:221], off
	s_add_i32 m0, s36, 0x2000
	s_add_u32 s34, s34, 0x40080
	v_lshl_add_u64 v[220:221], v[222:223], 0, s[94:95]
	s_addc_u32 s35, s35, 0
	s_add_i32 s36, s41, s59
	global_load_lds_dwordx4 v[220:221], off
	v_lshl_add_u64 v[220:221], s[34:35], 0, v[0:1]
	s_mov_b32 m0, s36
	s_nop 0
	global_load_lds_dwordx4 v[220:221], off
	v_lshl_add_u64 v[220:221], s[34:35], 0, v[166:167]
	s_add_i32 m0, s36, 0x2000
	s_nop 0
	global_load_lds_dwordx4 v[220:221], off
	v_lshl_add_u64 v[220:221], v[224:225], 0, s[94:95]
	s_mov_b32 m0, s88
	s_nop 0
	global_load_lds_dwordx4 v[220:221], off
	v_lshl_add_u64 v[220:221], v[226:227], 0, s[94:95]
	s_mov_b32 m0, s89
	s_nop 0
	global_load_lds_dwordx4 v[220:221], off
	s_waitcnt vmcnt(8)
	s_waitcnt lgkmcnt(0)
	s_barrier
	s_waitcnt lgkmcnt(0)
	v_mfma_f32_16x16x32_bf16 v[62:65], v[130:133], v[172:175], v[62:65]
	v_mfma_f32_16x16x32_bf16 v[58:61], v[138:141], v[172:175], v[58:61]
	v_mfma_f32_16x16x32_bf16 v[54:57], v[130:133], v[180:183], v[54:57]
	v_mfma_f32_16x16x32_bf16 v[50:53], v[138:141], v[180:183], v[50:53]
	v_mfma_f32_16x16x32_bf16 v[38:41], v[130:133], v[190:193], v[38:41]
	v_mfma_f32_16x16x32_bf16 v[34:37], v[138:141], v[190:193], v[34:37]
	v_mfma_f32_16x16x32_bf16 v[22:25], v[130:133], v[212:215], v[22:25]
	v_mfma_f32_16x16x32_bf16 v[18:21], v[138:141], v[212:215], v[18:21]
	v_mfma_f32_16x16x32_bf16 v[62:65], v[134:137], v[176:179], v[62:65]
	v_mfma_f32_16x16x32_bf16 v[58:61], v[142:145], v[176:179], v[58:61]
	v_mfma_f32_16x16x32_bf16 v[54:57], v[134:137], v[184:187], v[54:57]
	v_mfma_f32_16x16x32_bf16 v[50:53], v[142:145], v[184:187], v[50:53]
	v_mfma_f32_16x16x32_bf16 v[38:41], v[134:137], v[208:211], v[38:41]
	v_mfma_f32_16x16x32_bf16 v[34:37], v[142:145], v[208:211], v[34:37]
	v_mfma_f32_16x16x32_bf16 v[22:25], v[134:137], v[216:219], v[22:25]
	v_mfma_f32_16x16x32_bf16 v[18:21], v[142:145], v[216:219], v[18:21]
	v_mfma_f32_16x16x32_bf16 v[46:49], v[146:149], v[172:175], v[46:49]
	v_mfma_f32_16x16x32_bf16 v[42:45], v[154:157], v[172:175], v[42:45]
	v_mfma_f32_16x16x32_bf16 v[30:33], v[146:149], v[180:183], v[30:33]
	v_mfma_f32_16x16x32_bf16 v[26:29], v[154:157], v[180:183], v[26:29]
	v_mfma_f32_16x16x32_bf16 v[14:17], v[146:149], v[190:193], v[14:17]
	v_mfma_f32_16x16x32_bf16 v[10:13], v[154:157], v[190:193], v[10:13]
	v_mfma_f32_16x16x32_bf16 v[6:9], v[146:149], v[212:215], v[6:9]
	v_mfma_f32_16x16x32_bf16 v[2:5], v[154:157], v[212:215], v[2:5]
	v_mfma_f32_16x16x32_bf16 v[46:49], v[150:153], v[176:179], v[46:49]
	v_mfma_f32_16x16x32_bf16 v[42:45], v[158:161], v[176:179], v[42:45]
	v_mfma_f32_16x16x32_bf16 v[30:33], v[150:153], v[184:187], v[30:33]
	v_mfma_f32_16x16x32_bf16 v[26:29], v[158:161], v[184:187], v[26:29]
	v_mfma_f32_16x16x32_bf16 v[14:17], v[150:153], v[208:211], v[14:17]
	v_mfma_f32_16x16x32_bf16 v[10:13], v[158:161], v[208:211], v[10:13]
	v_mfma_f32_16x16x32_bf16 v[6:9], v[150:153], v[216:219], v[6:9]
	v_mfma_f32_16x16x32_bf16 v[2:5], v[158:161], v[216:219], v[2:5]
	s_add_u32 vcc_hi, vcc_hi, 0x100
	s_addc_u32 s63, s63, 0
	s_add_u32 s30, s30, 0x100
	s_addc_u32 s31, s31, 0
	s_cmp_ge_i32 s56, s1
	s_mov_b32 s34, s56
	s_cbranch_scc1 .Lrot_exit_1
	s_add_i32 s56, s34, 2
	s_add_u32 s35, s30, 0xfffc0080
	s_addc_u32 s36, s31, -1
	s_add_i32 s40, 0, 0x10000
	s_cmp_eq_u32 vcc_lo, s34
	s_cselect_b32 s37, s15, s36
	s_cselect_b32 s36, s19, s35
	s_cselect_b32 s35, s17, s63
	s_cselect_b32 s34, s27, vcc_hi
	s_add_i32 s42, 0, 0x14000
	v_add_u32_e32 v142, s40, v188
	v_add_u32_e32 v158, s42, v188
	s_barrier
	s_branch .Lrot_1
.Lrot_exit_1:
	s_barrier
	s_setprio 0
	s_and_b64 vcc, exec, s[12:13]
	s_cbranch_vccz .LBB0_851
	s_barrier

; #define PG8_STAGE(bufoff, gbase, voff) do { _Pragma("unroll") for (int _i = 0; _i < 2; ++_i) \
;         __builtin_amdgcn_global_load_lds((const unsigned*)((const char*)(gbase) + (voff)[_i]), (PG8_LAS unsigned*)(lds + (bufoff) + ldsw + _i * 8192), 16, 0, 0); } while (0)
; #define PG8_LDA(dst, b, h) do { _Pragma("unroll") for (int m = 0; m < 4; ++m) _Pragma("unroll") for (int k = 0; k < 2; ++k) dst[m][k] = *(const PG8_LAS bf16x8*)(lds + PG8_SA(b, h) + aoff + m * 2048 + k * 1024); } while (0)
; #define PG8_LDB(dst, b, h) do { _Pragma("unroll") for (int n = 0; n < 2; ++n) _Pragma("unroll") for (int k = 0; k < 2; ++k) dst[n][k] = *(const PG8_LAS bf16x8*)(lds + PG8_SB(b, h) + boff + n * 2048 + k * 1024); } while (0)
; #define PG8_MMA(ai, bj, At, Bt) do { __builtin_amdgcn_s_setprio(1); _Pragma("unroll") for (int m = 0; m < 4; ++m) _Pragma("unroll") for (int n = 0; n < 2; ++n) _Pragma("unroll") for (int k = 0; k < 2; ++k) \
;         acc[ai][bj][m][n] = __builtin_amdgcn_mfma_f32_16x16x32_bf16(Bt[n][k], At[m][k], acc[ai][bj][m][n], 0, 0, 0); __builtin_amdgcn_s_setprio(0); } while (0)
; #define PG8_WAIT_V(n) asm volatile("s_waitcnt vmcnt(" #n ")" ::: "memory")
; #define PG8_WAIT_L(n) asm volatile("s_waitcnt lgkmcnt(" #n ")" ::: "memory")
; #define PG8_BAR __builtin_amdgcn_s_barrier()
; #define PG8_SCHED __builtin_amdgcn_sched_barrier(0)
; template <class Epi, class Sched, bool ALIGN_EPI = false, bool SP2 = false>
; __device__ __forceinline__ void gemm_phase(PG8_LAS unsigned char* lds, const Gemm g, const Sched& S, const Epi& E, int wid_in) {
;     ...
;             PG8_LDB(B0, 0, 0); PG8_LDB(B1, 0, 1); PG8_SCHED; PG8_LDA(At, 0, 0); PG8_STAGE(PG8_SA(1, 1), a1 + hstep, voffA);
;             PG8_WAIT_V(8); PG8_WAIT_L(0); PG8_BAR; PG8_MMA(0, 0, At, B0); PG8_MMA(0, 1, At, B1); PG8_BAR; PG8_SCHED;
;             PG8_LDA(At, 0, 1); PG8_STAGE(PG8_SB(0, 0), b2, voffB); PG8_STAGE(PG8_SB(0, 1), b2 + hstep, voffB); PG8_STAGE(PG8_SA(0, 0), a2, voffA);
;             PG8_WAIT_V(8); PG8_WAIT_L(0); PG8_BAR; PG8_MMA(1, 0, At, B0); PG8_MMA(1, 1, At, B1); PG8_BAR; PG8_SCHED;
.Lrot_2:
	ds_read_b128 v[130:133], v142
	ds_read_b128 v[134:137], v142 offset:1024
	ds_read_b128 v[138:141], v142 offset:2048
	ds_read_b128 v[142:145], v142 offset:3072
	ds_read_b128 v[146:149], v158
	ds_read_b128 v[150:153], v158 offset:1024
	ds_read_b128 v[154:157], v158 offset:2048
	ds_read_b128 v[158:161], v158 offset:3072
	v_lshl_add_u64 v[218:219], s[30:31], 0, v[216:217]
	s_add_i32 m0, s29, 0xc000
	ds_read_b128 v[162:165], v251
	ds_read_b128 v[166:169], v251 offset:1024
	ds_read_b128 v[170:173], v251 offset:2048
	ds_read_b128 v[174:177], v251 offset:3072
	ds_read_b128 v[178:181], v251 offset:4096
	ds_read_b128 v[182:185], v251 offset:5120
	ds_read_b128 v[186:189], v251 offset:6144
	ds_read_b128 v[190:193], v251 offset:7168
	global_load_lds_dwordx4 v[218:219], off
	v_lshl_add_u64 v[218:219], s[30:31], 0, v[214:215]
	s_add_i32 m0, s29, 0xe000
	s_nop 0
	global_load_lds_dwordx4 v[218:219], off
	s_waitcnt vmcnt(8)
	s_waitcnt lgkmcnt(0)
	s_barrier
	s_waitcnt lgkmcnt(0)
	v_mfma_f32_16x16x32_bf16 v[126:129], v[130:133], v[162:165], v[126:129]
	v_mfma_f32_16x16x32_bf16 v[122:125], v[138:141], v[162:165], v[122:125]
	v_mfma_f32_16x16x32_bf16 v[118:121], v[130:133], v[170:173], v[118:121]
	v_mfma_f32_16x16x32_bf16 v[114:117], v[138:141], v[170:173], v[114:117]
	v_mfma_f32_16x16x32_bf16 v[102:105], v[130:133], v[178:181], v[102:105]
	v_mfma_f32_16x16x32_bf16 v[98:101], v[138:141], v[178:181], v[98:101]
	v_mfma_f32_16x16x32_bf16 v[86:89], v[130:133], v[186:189], v[86:89]
	v_mfma_f32_16x16x32_bf16 v[82:85], v[138:141], v[186:189], v[82:85]
	v_mfma_f32_16x16x32_bf16 v[126:129], v[134:137], v[166:169], v[126:129]
	v_mfma_f32_16x16x32_bf16 v[122:125], v[142:145], v[166:169], v[122:125]
	v_mfma_f32_16x16x32_bf16 v[118:121], v[134:137], v[174:177], v[118:121]
	v_mfma_f32_16x16x32_bf16 v[114:117], v[142:145], v[174:177], v[114:117]
	v_mfma_f32_16x16x32_bf16 v[102:105], v[134:137], v[182:185], v[102:105]
	v_mfma_f32_16x16x32_bf16 v[98:101], v[142:145], v[182:185], v[98:101]
	v_mfma_f32_16x16x32_bf16 v[86:89], v[134:137], v[190:193], v[86:89]
	v_mfma_f32_16x16x32_bf16 v[82:85], v[142:145], v[190:193], v[82:85]
	v_mfma_f32_16x16x32_bf16 v[110:113], v[146:149], v[162:165], v[110:113]
	v_mfma_f32_16x16x32_bf16 v[106:109], v[154:157], v[162:165], v[106:109]
	v_mfma_f32_16x16x32_bf16 v[94:97], v[146:149], v[170:173], v[94:97]
	v_mfma_f32_16x16x32_bf16 v[90:93], v[154:157], v[170:173], v[90:93]
	v_mfma_f32_16x16x32_bf16 v[78:81], v[146:149], v[178:181], v[78:81]
	v_mfma_f32_16x16x32_bf16 v[74:77], v[154:157], v[178:181], v[74:77]
	v_mfma_f32_16x16x32_bf16 v[70:73], v[146:149], v[186:189], v[70:73]
	v_mfma_f32_16x16x32_bf16 v[66:69], v[154:157], v[186:189], v[66:69]
	v_mfma_f32_16x16x32_bf16 v[110:113], v[150:153], v[166:169], v[110:113]
	v_mfma_f32_16x16x32_bf16 v[106:109], v[158:161], v[166:169], v[106:109]
	v_mfma_f32_16x16x32_bf16 v[94:97], v[150:153], v[174:177], v[94:97]
	v_mfma_f32_16x16x32_bf16 v[90:93], v[158:161], v[174:177], v[90:93]
	v_mfma_f32_16x16x32_bf16 v[78:81], v[150:153], v[182:185], v[78:81]
	v_mfma_f32_16x16x32_bf16 v[74:77], v[158:161], v[182:185], v[74:77]
	v_mfma_f32_16x16x32_bf16 v[70:73], v[150:153], v[190:193], v[70:73]
	v_mfma_f32_16x16x32_bf16 v[66:69], v[158:161], v[190:193], v[66:69]
	s_barrier
	s_add_i32 s40, s40, s59
	v_lshl_add_u64 v[218:219], s[34:35], 0, v[0:1]
	s_mov_b32 m0, s40
	ds_read_b128 v[162:165], v251 offset:16384
	ds_read_b128 v[166:169], v251 offset:17408
	ds_read_b128 v[170:173], v251 offset:18432
	ds_read_b128 v[174:177], v251 offset:19456
	ds_read_b128 v[178:181], v251 offset:20480
	ds_read_b128 v[182:185], v251 offset:21504
	ds_read_b128 v[186:189], v251 offset:22528
	ds_read_b128 v[190:193], v251 offset:23552
	global_load_lds_dwordx4 v[218:219], off
	s_add_i32 m0, s40, 0x2000
	s_add_u32 s40, s34, 0x40000
	v_lshl_add_u64 v[220:221], s[34:35], 0, v[212:213]
	s_addc_u32 s41, s35, 0
	s_add_i32 s42, s42, s59
	global_load_lds_dwordx4 v[220:221], off
	v_lshl_add_u64 v[222:223], s[40:41], 0, v[0:1]
	s_mov_b32 m0, s42
	v_lshl_add_u64 v[224:225], s[36:37], 0, v[210:211]
	global_load_lds_dwordx4 v[222:223], off
	v_lshl_add_u64 v[222:223], s[40:41], 0, v[212:213]
	s_add_i32 m0, s42, 0x2000
	s_nop 0
	global_load_lds_dwordx4 v[222:223], off
	v_lshl_add_u64 v[222:223], s[36:37], 0, v[208:209]
	s_mov_b32 m0, s29
	s_nop 0
	global_load_lds_dwordx4 v[222:223], off
	s_mov_b32 m0, s48
	s_nop 0
	global_load_lds_dwordx4 v[224:225], off
	s_waitcnt vmcnt(8)
	s_waitcnt lgkmcnt(0)
	s_barrier
	s_waitcnt lgkmcnt(0)
	v_mfma_f32_16x16x32_bf16 v[62:65], v[130:133], v[162:165], v[62:65]
	v_mfma_f32_16x16x32_bf16 v[58:61], v[138:141], v[162:165], v[58:61]
	v_mfma_f32_16x16x32_bf16 v[54:57], v[130:133], v[170:173], v[54:57]
	v_mfma_f32_16x16x32_bf16 v[50:53], v[138:141], v[170:173], v[50:53]
	v_mfma_f32_16x16x32_bf16 v[38:41], v[130:133], v[178:181], v[38:41]
	v_mfma_f32_16x16x32_bf16 v[34:37], v[138:141], v[178:181], v[34:37]
	v_mfma_f32_16x16x32_bf16 v[22:25], v[130:133], v[186:189], v[22:25]
	v_mfma_f32_16x16x32_bf16 v[18:21], v[138:141], v[186:189], v[18:21]
	v_mfma_f32_16x16x32_bf16 v[62:65], v[134:137], v[166:169], v[62:65]
	v_mfma_f32_16x16x32_bf16 v[58:61], v[142:145], v[166:169], v[58:61]
	v_mfma_f32_16x16x32_bf16 v[54:57], v[134:137], v[174:177], v[54:57]
	v_mfma_f32_16x16x32_bf16 v[50:53], v[142:145], v[174:177], v[50:53]
	v_mfma_f32_16x16x32_bf16 v[38:41], v[134:137], v[182:185], v[38:41]
	v_mfma_f32_16x16x32_bf16 v[34:37], v[142:145], v[182:185], v[34:37]
	v_mfma_f32_16x16x32_bf16 v[22:25], v[134:137], v[190:193], v[22:25]
	v_mfma_f32_16x16x32_bf16 v[18:21], v[142:145], v[190:193], v[18:21]
	v_mfma_f32_16x16x32_bf16 v[46:49], v[146:149], v[162:165], v[46:49]
	v_mfma_f32_16x16x32_bf16 v[42:45], v[154:157], v[162:165], v[42:45]
	v_mfma_f32_16x16x32_bf16 v[30:33], v[146:149], v[170:173], v[30:33]
	v_mfma_f32_16x16x32_bf16 v[26:29], v[154:157], v[170:173], v[26:29]
	v_mfma_f32_16x16x32_bf16 v[14:17], v[146:149], v[178:181], v[14:17]
	v_mfma_f32_16x16x32_bf16 v[10:13], v[154:157], v[178:181], v[10:13]
	v_mfma_f32_16x16x32_bf16 v[6:9], v[146:149], v[186:189], v[6:9]
	v_mfma_f32_16x16x32_bf16 v[2:5], v[154:157], v[186:189], v[2:5]
	v_mfma_f32_16x16x32_bf16 v[46:49], v[150:153], v[166:169], v[46:49]
	v_mfma_f32_16x16x32_bf16 v[42:45], v[158:161], v[166:169], v[42:45]
	v_mfma_f32_16x16x32_bf16 v[30:33], v[150:153], v[174:177], v[30:33]
	v_mfma_f32_16x16x32_bf16 v[26:29], v[158:161], v[174:177], v[26:29]
	v_mfma_f32_16x16x32_bf16 v[14:17], v[150:153], v[182:185], v[14:17]
	v_mfma_f32_16x16x32_bf16 v[10:13], v[158:161], v[182:185], v[10:13]
	v_mfma_f32_16x16x32_bf16 v[6:9], v[150:153], v[190:193], v[6:9]
	v_mfma_f32_16x16x32_bf16 v[2:5], v[158:161], v[190:193], v[2:5]
	s_barrier
; #define PG8_STAGE(bufoff, gbase, voff) do { _Pragma("unroll") for (int _i = 0; _i < 2; ++_i) \
;         __builtin_amdgcn_global_load_lds((const unsigned*)((const char*)(gbase) + (voff)[_i]), (PG8_LAS unsigned*)(lds + (bufoff) + ldsw + _i * 8192), 16, 0, 0); } while (0)
; #define PG8_LDA(dst, b, h) do { _Pragma("unroll") for (int m = 0; m < 4; ++m) _Pragma("unroll") for (int k = 0; k < 2; ++k) dst[m][k] = *(const PG8_LAS bf16x8*)(lds + PG8_SA(b, h) + aoff + m * 2048 + k * 1024); } while (0)
; #define PG8_LDB(dst, b, h) do { _Pragma("unroll") for (int n = 0; n < 2; ++n) _Pragma("unroll") for (int k = 0; k < 2; ++k) dst[n][k] = *(const PG8_LAS bf16x8*)(lds + PG8_SB(b, h) + boff + n * 2048 + k * 1024); } while (0)
; #define PG8_MMA(ai, bj, At, Bt) do { __builtin_amdgcn_s_setprio(1); _Pragma("unroll") for (int m = 0; m < 4; ++m) _Pragma("unroll") for (int n = 0; n < 2; ++n) _Pragma("unroll") for (int k = 0; k < 2; ++k) \
;         acc[ai][bj][m][n] = __builtin_amdgcn_mfma_f32_16x16x32_bf16(Bt[n][k], At[m][k], acc[ai][bj][m][n], 0, 0, 0); __builtin_amdgcn_s_setprio(0); } while (0)
; #define PG8_WAIT_V(n) asm volatile("s_waitcnt vmcnt(" #n ")" ::: "memory")
; #define PG8_WAIT_L(n) asm volatile("s_waitcnt lgkmcnt(" #n ")" ::: "memory")
; #define PG8_BAR __builtin_amdgcn_s_barrier()
; #define PG8_SCHED __builtin_amdgcn_sched_barrier(0)
; template <class Epi, class Sched, bool ALIGN_EPI = false, bool SP2 = false>
; __device__ __forceinline__ void gemm_phase(PG8_LAS unsigned char* lds, const Gemm g, const Sched& S, const Epi& E, int wid_in) {
;     ...
;             PG8_LDB(B0, 1, 0); PG8_LDB(B1, 1, 1); PG8_SCHED; PG8_LDA(At, 1, 0); PG8_STAGE(PG8_SA(0, 1), a2 + hstep, voffA);
;             PG8_WAIT_V(8); PG8_WAIT_L(0); PG8_BAR; PG8_MMA(0, 0, At, B0); PG8_MMA(0, 1, At, B1); PG8_BAR; PG8_SCHED;
	s_add_i32 s40, 0, 0x18000
	s_add_i32 s41, 0, 0x1c000
	v_add_u32_e32 v142, s40, v195
	v_add_u32_e32 v158, s41, v195
	ds_read_b128 v[130:133], v142
	ds_read_b128 v[134:137], v142 offset:1024
	ds_read_b128 v[138:141], v142 offset:2048
	ds_read_b128 v[142:145], v142 offset:3072
	ds_read_b128 v[146:149], v158
	ds_read_b128 v[150:153], v158 offset:1024
	ds_read_b128 v[154:157], v158 offset:2048
	ds_read_b128 v[158:161], v158 offset:3072
	s_add_u32 s36, s36, 0x40000
	s_addc_u32 s37, s37, 0
	s_mov_b32 m0, s61
	v_lshl_add_u64 v[226:227], s[36:37], 0, v[208:209]
	ds_read_b128 v[162:165], v251 offset:32768
	ds_read_b128 v[166:169], v251 offset:33792
	ds_read_b128 v[170:173], v251 offset:34816
	ds_read_b128 v[174:177], v251 offset:35840
	ds_read_b128 v[178:181], v251 offset:36864
	ds_read_b128 v[182:185], v251 offset:37888
	ds_read_b128 v[186:189], v251 offset:38912
	ds_read_b128 v[190:193], v251 offset:39936
	global_load_lds_dwordx4 v[226:227], off
	v_lshl_add_u64 v[226:227], s[36:37], 0, v[210:211]
	s_mov_b32 m0, s62
	s_nop 0
	global_load_lds_dwordx4 v[226:227], off
	s_waitcnt vmcnt(8)
	s_waitcnt lgkmcnt(0)
	s_barrier
	s_waitcnt lgkmcnt(0)
	v_mfma_f32_16x16x32_bf16 v[126:129], v[130:133], v[162:165], v[126:129]
	v_mfma_f32_16x16x32_bf16 v[122:125], v[138:141], v[162:165], v[122:125]
	v_mfma_f32_16x16x32_bf16 v[118:121], v[130:133], v[170:173], v[118:121]
	v_mfma_f32_16x16x32_bf16 v[114:117], v[138:141], v[170:173], v[114:117]
	v_mfma_f32_16x16x32_bf16 v[102:105], v[130:133], v[178:181], v[102:105]
	v_mfma_f32_16x16x32_bf16 v[98:101], v[138:141], v[178:181], v[98:101]
	v_mfma_f32_16x16x32_bf16 v[86:89], v[130:133], v[186:189], v[86:89]
	v_mfma_f32_16x16x32_bf16 v[82:85], v[138:141], v[186:189], v[82:85]
	v_mfma_f32_16x16x32_bf16 v[126:129], v[134:137], v[166:169], v[126:129]
	v_mfma_f32_16x16x32_bf16 v[122:125], v[142:145], v[166:169], v[122:125]
	v_mfma_f32_16x16x32_bf16 v[118:121], v[134:137], v[174:177], v[118:121]
	v_mfma_f32_16x16x32_bf16 v[114:117], v[142:145], v[174:177], v[114:117]
	v_mfma_f32_16x16x32_bf16 v[102:105], v[134:137], v[182:185], v[102:105]
	v_mfma_f32_16x16x32_bf16 v[98:101], v[142:145], v[182:185], v[98:101]
	v_mfma_f32_16x16x32_bf16 v[86:89], v[134:137], v[190:193], v[86:89]
	v_mfma_f32_16x16x32_bf16 v[82:85], v[142:145], v[190:193], v[82:85]
	v_mfma_f32_16x16x32_bf16 v[110:113], v[146:149], v[162:165], v[110:113]
	v_mfma_f32_16x16x32_bf16 v[106:109], v[154:157], v[162:165], v[106:109]
	v_mfma_f32_16x16x32_bf16 v[94:97], v[146:149], v[170:173], v[94:97]
	v_mfma_f32_16x16x32_bf16 v[90:93], v[154:157], v[170:173], v[90:93]
	v_mfma_f32_16x16x32_bf16 v[78:81], v[146:149], v[178:181], v[78:81]
	v_mfma_f32_16x16x32_bf16 v[74:77], v[154:157], v[178:181], v[74:77]
	v_mfma_f32_16x16x32_bf16 v[70:73], v[146:149], v[186:189], v[70:73]
	v_mfma_f32_16x16x32_bf16 v[66:69], v[154:157], v[186:189], v[66:69]
	v_mfma_f32_16x16x32_bf16 v[110:113], v[150:153], v[166:169], v[110:113]
	v_mfma_f32_16x16x32_bf16 v[106:109], v[158:161], v[166:169], v[106:109]
	v_mfma_f32_16x16x32_bf16 v[94:97], v[150:153], v[174:177], v[94:97]
	v_mfma_f32_16x16x32_bf16 v[90:93], v[158:161], v[174:177], v[90:93]
	v_mfma_f32_16x16x32_bf16 v[78:81], v[150:153], v[182:185], v[78:81]
	v_mfma_f32_16x16x32_bf16 v[74:77], v[158:161], v[182:185], v[74:77]
	v_mfma_f32_16x16x32_bf16 v[70:73], v[150:153], v[190:193], v[70:73]
	v_mfma_f32_16x16x32_bf16 v[66:69], v[158:161], v[190:193], v[66:69]
	s_barrier
; #define PG8_STAGE(bufoff, gbase, voff) do { _Pragma("unroll") for (int _i = 0; _i < 2; ++_i) \
;         __builtin_amdgcn_global_load_lds((const unsigned*)((const char*)(gbase) + (voff)[_i]), (PG8_LAS unsigned*)(lds + (bufoff) + ldsw + _i * 8192), 16, 0, 0); } while (0)
; #define PG8_LDA(dst, b, h) do { _Pragma("unroll") for (int m = 0; m < 4; ++m) _Pragma("unroll") for (int k = 0; k < 2; ++k) dst[m][k] = *(const PG8_LAS bf16x8*)(lds + PG8_SA(b, h) + aoff + m * 2048 + k * 1024); } while (0)
; #define PG8_MMA(ai, bj, At, Bt) do { __builtin_amdgcn_s_setprio(1); _Pragma("unroll") for (int m = 0; m < 4; ++m) _Pragma("unroll") for (int n = 0; n < 2; ++n) _Pragma("unroll") for (int k = 0; k < 2; ++k) \
;         acc[ai][bj][m][n] = __builtin_amdgcn_mfma_f32_16x16x32_bf16(Bt[n][k], At[m][k], acc[ai][bj][m][n], 0, 0, 0); __builtin_amdgcn_s_setprio(0); } while (0)
; #define PG8_WAIT_V(n) asm volatile("s_waitcnt vmcnt(" #n ")" ::: "memory")
; #define PG8_WAIT_L(n) asm volatile("s_waitcnt lgkmcnt(" #n ")" ::: "memory")
; #define PG8_BAR __builtin_amdgcn_s_barrier()
; #define PG8_SCHED __builtin_amdgcn_sched_barrier(0)
; template <class Epi, class Sched, bool ALIGN_EPI = false, bool SP2 = false>
; __device__ __forceinline__ void gemm_phase(PG8_LAS unsigned char* lds, const Gemm g, const Sched& S, const Epi& E, int wid_in) {
;     ...
;         for (int t = 0; t < nt; t += 2) {
;             const bool last = (t == nt - 2);
;             const char* a1 = cA + (size_t)(t + 1) * kstep;
;             const char* a2 = last ? nA : cA + (size_t)(t + 2) * kstep; const char* b2 = last ? nB : cB + (size_t)(t + 2) * kstep;
;             const char* a3 = a2 + kstep; const char* b3 = b2 + kstep;
;     ...
;             PG8_LDA(At, 1, 1); PG8_STAGE(PG8_SB(1, 0), b3, voffB); PG8_STAGE(PG8_SB(1, 1), b3 + hstep, voffB); PG8_STAGE(PG8_SA(1, 0), a3, voffA);
;             PG8_WAIT_V(8); PG8_WAIT_L(0); PG8_BAR; PG8_MMA(1, 0, At, B0); PG8_MMA(1, 1, At, B1); PG8_BAR; PG8_SCHED;
	s_add_i32 s36, s40, s59
	v_lshl_add_u64 v[218:219], v[218:219], 0, s[94:95]
	s_mov_b32 m0, s36
	ds_read_b128 v[162:165], v251 offset:49152
	ds_read_b128 v[166:169], v251 offset:50176
	ds_read_b128 v[170:173], v251 offset:51200
	ds_read_b128 v[174:177], v251 offset:52224
	ds_read_b128 v[178:181], v251 offset:53248
	ds_read_b128 v[182:185], v251 offset:54272
	ds_read_b128 v[186:189], v251 offset:55296
	ds_read_b128 v[190:193], v251 offset:56320
	global_load_lds_dwordx4 v[218:219], off
	s_add_i32 m0, s36, 0x2000
	s_add_u32 s34, s34, 0x40080
	v_lshl_add_u64 v[218:219], v[220:221], 0, s[94:95]
	s_addc_u32 s35, s35, 0
	s_add_i32 s36, s41, s59
	global_load_lds_dwordx4 v[218:219], off
	v_lshl_add_u64 v[218:219], s[34:35], 0, v[0:1]
	s_mov_b32 m0, s36
	s_nop 0
	global_load_lds_dwordx4 v[218:219], off
	v_lshl_add_u64 v[218:219], s[34:35], 0, v[212:213]
	s_add_i32 m0, s36, 0x2000
	s_nop 0
	global_load_lds_dwordx4 v[218:219], off
	v_lshl_add_u64 v[218:219], v[222:223], 0, s[94:95]
	s_mov_b32 m0, s89
	s_nop 0
	global_load_lds_dwordx4 v[218:219], off
	v_lshl_add_u64 v[218:219], v[224:225], 0, s[94:95]
	s_mov_b32 m0, s90
	s_nop 0
	global_load_lds_dwordx4 v[218:219], off
	s_waitcnt vmcnt(8)
	s_waitcnt lgkmcnt(0)
	s_barrier
	s_waitcnt lgkmcnt(0)
	v_mfma_f32_16x16x32_bf16 v[62:65], v[130:133], v[162:165], v[62:65]
	v_mfma_f32_16x16x32_bf16 v[58:61], v[138:141], v[162:165], v[58:61]
	v_mfma_f32_16x16x32_bf16 v[54:57], v[130:133], v[170:173], v[54:57]
	v_mfma_f32_16x16x32_bf16 v[50:53], v[138:141], v[170:173], v[50:53]
	v_mfma_f32_16x16x32_bf16 v[38:41], v[130:133], v[178:181], v[38:41]
	v_mfma_f32_16x16x32_bf16 v[34:37], v[138:141], v[178:181], v[34:37]
	v_mfma_f32_16x16x32_bf16 v[22:25], v[130:133], v[186:189], v[22:25]
	v_mfma_f32_16x16x32_bf16 v[18:21], v[138:141], v[186:189], v[18:21]
	v_mfma_f32_16x16x32_bf16 v[62:65], v[134:137], v[166:169], v[62:65]
	v_mfma_f32_16x16x32_bf16 v[58:61], v[142:145], v[166:169], v[58:61]
	v_mfma_f32_16x16x32_bf16 v[54:57], v[134:137], v[174:177], v[54:57]
	v_mfma_f32_16x16x32_bf16 v[50:53], v[142:145], v[174:177], v[50:53]
	v_mfma_f32_16x16x32_bf16 v[38:41], v[134:137], v[182:185], v[38:41]
	v_mfma_f32_16x16x32_bf16 v[34:37], v[142:145], v[182:185], v[34:37]
	v_mfma_f32_16x16x32_bf16 v[22:25], v[134:137], v[190:193], v[22:25]
	v_mfma_f32_16x16x32_bf16 v[18:21], v[142:145], v[190:193], v[18:21]
	v_mfma_f32_16x16x32_bf16 v[46:49], v[146:149], v[162:165], v[46:49]
	v_mfma_f32_16x16x32_bf16 v[42:45], v[154:157], v[162:165], v[42:45]
	v_mfma_f32_16x16x32_bf16 v[30:33], v[146:149], v[170:173], v[30:33]
	v_mfma_f32_16x16x32_bf16 v[26:29], v[154:157], v[170:173], v[26:29]
	v_mfma_f32_16x16x32_bf16 v[14:17], v[146:149], v[178:181], v[14:17]
	v_mfma_f32_16x16x32_bf16 v[10:13], v[154:157], v[178:181], v[10:13]
	v_mfma_f32_16x16x32_bf16 v[6:9], v[146:149], v[186:189], v[6:9]
	v_mfma_f32_16x16x32_bf16 v[2:5], v[154:157], v[186:189], v[2:5]
	v_mfma_f32_16x16x32_bf16 v[46:49], v[150:153], v[166:169], v[46:49]
	v_mfma_f32_16x16x32_bf16 v[42:45], v[158:161], v[166:169], v[42:45]
	v_mfma_f32_16x16x32_bf16 v[30:33], v[150:153], v[174:177], v[30:33]
	v_mfma_f32_16x16x32_bf16 v[26:29], v[158:161], v[174:177], v[26:29]
	v_mfma_f32_16x16x32_bf16 v[14:17], v[150:153], v[182:185], v[14:17]
	v_mfma_f32_16x16x32_bf16 v[10:13], v[158:161], v[182:185], v[10:13]
	v_mfma_f32_16x16x32_bf16 v[6:9], v[150:153], v[190:193], v[6:9]
	v_mfma_f32_16x16x32_bf16 v[2:5], v[158:161], v[190:193], v[2:5]
	s_add_u32 vcc_hi, vcc_hi, 0x100
	s_addc_u32 s63, s63, 0
	s_add_u32 s30, s30, 0x100
	s_addc_u32 s31, s31, 0
	s_cmp_ge_i32 s56, s1
	s_mov_b32 s34, s56
	s_cbranch_scc1 .Lrot_exit_2
	s_add_i32 s56, s34, 2
	s_add_u32 s35, s30, 0xfffc0080
	s_addc_u32 s36, s31, -1
	s_add_i32 s40, 0, 0x10000
	s_cmp_eq_u32 vcc_lo, s34
	s_cselect_b32 s37, s15, s36
	s_cselect_b32 s36, s19, s35
	s_cselect_b32 s35, s17, s63
	s_cselect_b32 s34, s27, vcc_hi
	s_add_i32 s42, 0, 0x14000
	v_add_u32_e32 v142, s40, v195
	v_add_u32_e32 v158, s42, v195
	s_barrier
	s_branch .Lrot_2

; #define PG8_STAGE(bufoff, gbase, voff) do { _Pragma("unroll") for (int _i = 0; _i < 2; ++_i) \
;         __builtin_amdgcn_global_load_lds((const unsigned*)((const char*)(gbase) + (voff)[_i]), (PG8_LAS unsigned*)(lds + (bufoff) + ldsw + _i * 8192), 16, 0, 0); } while (0)
; #define PG8_LDA(dst, b, h) do { _Pragma("unroll") for (int m = 0; m < 4; ++m) _Pragma("unroll") for (int k = 0; k < 2; ++k) dst[m][k] = *(const PG8_LAS bf16x8*)(lds + PG8_SA(b, h) + aoff + m * 2048 + k * 1024); } while (0)
; #define PG8_LDB(dst, b, h) do { _Pragma("unroll") for (int n = 0; n < 2; ++n) _Pragma("unroll") for (int k = 0; k < 2; ++k) dst[n][k] = *(const PG8_LAS bf16x8*)(lds + PG8_SB(b, h) + boff + n * 2048 + k * 1024); } while (0)
; #define PG8_MMA(ai, bj, At, Bt) do { __builtin_amdgcn_s_setprio(1); _Pragma("unroll") for (int m = 0; m < 4; ++m) _Pragma("unroll") for (int n = 0; n < 2; ++n) _Pragma("unroll") for (int k = 0; k < 2; ++k) \
;         acc[ai][bj][m][n] = __builtin_amdgcn_mfma_f32_16x16x32_bf16(Bt[n][k], At[m][k], acc[ai][bj][m][n], 0, 0, 0); __builtin_amdgcn_s_setprio(0); } while (0)
; #define PG8_WAIT_V(n) asm volatile("s_waitcnt vmcnt(" #n ")" ::: "memory")
; #define PG8_WAIT_L(n) asm volatile("s_waitcnt lgkmcnt(" #n ")" ::: "memory")
; #define PG8_BAR __builtin_amdgcn_s_barrier()
; #define PG8_SCHED __builtin_amdgcn_sched_barrier(0)
; template <class Epi, class Sched, bool ALIGN_EPI = false, bool SP2 = false>
; __device__ __forceinline__ void gemm_phase(PG8_LAS unsigned char* lds, const Gemm g, const Sched& S, const Epi& E, int wid_in) {
;     ...
;             PG8_LDB(B0, 0, 0); PG8_LDB(B1, 0, 1); PG8_SCHED; PG8_LDA(At, 0, 0); PG8_STAGE(PG8_SA(1, 1), a1 + hstep, voffA);
;             PG8_WAIT_V(8); PG8_WAIT_L(0); PG8_BAR; PG8_MMA(0, 0, At, B0); PG8_MMA(0, 1, At, B1); PG8_BAR; PG8_SCHED;
;             PG8_LDA(At, 0, 1); PG8_STAGE(PG8_SB(0, 0), b2, voffB); PG8_STAGE(PG8_SB(0, 1), b2 + hstep, voffB); PG8_STAGE(PG8_SA(0, 0), a2, voffA);
;             PG8_WAIT_V(8); PG8_WAIT_L(0); PG8_BAR; PG8_MMA(1, 0, At, B0); PG8_MMA(1, 1, At, B1); PG8_BAR; PG8_SCHED;
.Lrot_3:
	ds_read_b128 v[130:133], v142
	ds_read_b128 v[134:137], v142 offset:1024
	ds_read_b128 v[138:141], v142 offset:2048
	ds_read_b128 v[142:145], v142 offset:3072
	ds_read_b128 v[146:149], v168
	ds_read_b128 v[160:163], v168 offset:1024
	ds_read_b128 v[164:167], v168 offset:2048
	ds_read_b128 v[168:171], v168 offset:3072
	v_lshl_add_u64 v[220:221], s[30:31], 0, v[158:159]
	s_add_i32 m0, s29, 0xc000
	ds_read_b128 v[172:175], v177
	ds_read_b128 v[178:181], v177 offset:1024
	ds_read_b128 v[182:185], v177 offset:2048
	ds_read_b128 v[186:189], v177 offset:3072
	ds_read_b128 v[190:193], v177 offset:4096
	ds_read_b128 v[208:211], v177 offset:5120
	ds_read_b128 v[212:215], v177 offset:6144
	ds_read_b128 v[216:219], v177 offset:7168
	global_load_lds_dwordx4 v[220:221], off
	v_lshl_add_u64 v[220:221], s[30:31], 0, v[156:157]
	s_add_i32 m0, s29, 0xe000
	s_nop 0
	global_load_lds_dwordx4 v[220:221], off
	s_waitcnt vmcnt(8)
	s_waitcnt lgkmcnt(0)
	s_barrier
	s_waitcnt lgkmcnt(0)
	v_mfma_f32_16x16x32_bf16 v[126:129], v[130:133], v[172:175], v[126:129]
	v_mfma_f32_16x16x32_bf16 v[122:125], v[138:141], v[172:175], v[122:125]
	v_mfma_f32_16x16x32_bf16 v[118:121], v[130:133], v[182:185], v[118:121]
	v_mfma_f32_16x16x32_bf16 v[114:117], v[138:141], v[182:185], v[114:117]
	v_mfma_f32_16x16x32_bf16 v[102:105], v[130:133], v[190:193], v[102:105]
	v_mfma_f32_16x16x32_bf16 v[98:101], v[138:141], v[190:193], v[98:101]
	v_mfma_f32_16x16x32_bf16 v[86:89], v[130:133], v[212:215], v[86:89]
	v_mfma_f32_16x16x32_bf16 v[82:85], v[138:141], v[212:215], v[82:85]
	v_mfma_f32_16x16x32_bf16 v[126:129], v[134:137], v[178:181], v[126:129]
	v_mfma_f32_16x16x32_bf16 v[122:125], v[142:145], v[178:181], v[122:125]
	v_mfma_f32_16x16x32_bf16 v[118:121], v[134:137], v[186:189], v[118:121]
	v_mfma_f32_16x16x32_bf16 v[114:117], v[142:145], v[186:189], v[114:117]
	v_mfma_f32_16x16x32_bf16 v[102:105], v[134:137], v[208:211], v[102:105]
	v_mfma_f32_16x16x32_bf16 v[98:101], v[142:145], v[208:211], v[98:101]
	v_mfma_f32_16x16x32_bf16 v[86:89], v[134:137], v[216:219], v[86:89]
	v_mfma_f32_16x16x32_bf16 v[82:85], v[142:145], v[216:219], v[82:85]
	v_mfma_f32_16x16x32_bf16 v[110:113], v[146:149], v[172:175], v[110:113]
	v_mfma_f32_16x16x32_bf16 v[106:109], v[164:167], v[172:175], v[106:109]
	v_mfma_f32_16x16x32_bf16 v[94:97], v[146:149], v[182:185], v[94:97]
	v_mfma_f32_16x16x32_bf16 v[90:93], v[164:167], v[182:185], v[90:93]
	v_mfma_f32_16x16x32_bf16 v[78:81], v[146:149], v[190:193], v[78:81]
	v_mfma_f32_16x16x32_bf16 v[74:77], v[164:167], v[190:193], v[74:77]
	v_mfma_f32_16x16x32_bf16 v[70:73], v[146:149], v[212:215], v[70:73]
	v_mfma_f32_16x16x32_bf16 v[66:69], v[164:167], v[212:215], v[66:69]
	v_mfma_f32_16x16x32_bf16 v[110:113], v[160:163], v[178:181], v[110:113]
	v_mfma_f32_16x16x32_bf16 v[106:109], v[168:171], v[178:181], v[106:109]
	v_mfma_f32_16x16x32_bf16 v[94:97], v[160:163], v[186:189], v[94:97]
	v_mfma_f32_16x16x32_bf16 v[90:93], v[168:171], v[186:189], v[90:93]
	v_mfma_f32_16x16x32_bf16 v[78:81], v[160:163], v[208:211], v[78:81]
	v_mfma_f32_16x16x32_bf16 v[74:77], v[168:171], v[208:211], v[74:77]
	v_mfma_f32_16x16x32_bf16 v[70:73], v[160:163], v[216:219], v[70:73]
	v_mfma_f32_16x16x32_bf16 v[66:69], v[168:171], v[216:219], v[66:69]
	s_barrier
	s_add_i32 s40, s40, s59
	v_lshl_add_u64 v[220:221], s[34:35], 0, v[0:1]
	s_mov_b32 m0, s40
	ds_read_b128 v[172:175], v177 offset:16384
	ds_read_b128 v[178:181], v177 offset:17408
	ds_read_b128 v[182:185], v177 offset:18432
	ds_read_b128 v[186:189], v177 offset:19456
	ds_read_b128 v[190:193], v177 offset:20480
	ds_read_b128 v[208:211], v177 offset:21504
	ds_read_b128 v[212:215], v177 offset:22528
	ds_read_b128 v[216:219], v177 offset:23552
	global_load_lds_dwordx4 v[220:221], off
	s_add_i32 m0, s40, 0x2000
	s_add_u32 s40, s34, 0x80000
	v_lshl_add_u64 v[222:223], s[34:35], 0, v[154:155]
	s_addc_u32 s41, s35, 0
	s_add_i32 s27, s27, s59
	global_load_lds_dwordx4 v[222:223], off
	v_lshl_add_u64 v[224:225], s[40:41], 0, v[0:1]
	s_mov_b32 m0, s27
	v_lshl_add_u64 v[226:227], s[36:37], 0, v[152:153]
	global_load_lds_dwordx4 v[224:225], off
	v_lshl_add_u64 v[224:225], s[40:41], 0, v[154:155]
	s_add_i32 m0, s27, 0x2000
	s_nop 0
	global_load_lds_dwordx4 v[224:225], off
	v_lshl_add_u64 v[224:225], s[36:37], 0, v[150:151]
	s_mov_b32 m0, s29
	s_nop 0
	global_load_lds_dwordx4 v[224:225], off
	s_mov_b32 m0, s52
	s_nop 0
	global_load_lds_dwordx4 v[226:227], off
	s_waitcnt vmcnt(8)
	s_waitcnt lgkmcnt(0)
	s_barrier
	s_waitcnt lgkmcnt(0)
	v_mfma_f32_16x16x32_bf16 v[62:65], v[130:133], v[172:175], v[62:65]
	v_mfma_f32_16x16x32_bf16 v[58:61], v[138:141], v[172:175], v[58:61]
	v_mfma_f32_16x16x32_bf16 v[54:57], v[130:133], v[182:185], v[54:57]
	v_mfma_f32_16x16x32_bf16 v[50:53], v[138:141], v[182:185], v[50:53]
	v_mfma_f32_16x16x32_bf16 v[38:41], v[130:133], v[190:193], v[38:41]
	v_mfma_f32_16x16x32_bf16 v[34:37], v[138:141], v[190:193], v[34:37]
	v_mfma_f32_16x16x32_bf16 v[22:25], v[130:133], v[212:215], v[22:25]
	v_mfma_f32_16x16x32_bf16 v[18:21], v[138:141], v[212:215], v[18:21]
	v_mfma_f32_16x16x32_bf16 v[62:65], v[134:137], v[178:181], v[62:65]
	v_mfma_f32_16x16x32_bf16 v[58:61], v[142:145], v[178:181], v[58:61]
	v_mfma_f32_16x16x32_bf16 v[54:57], v[134:137], v[186:189], v[54:57]
	v_mfma_f32_16x16x32_bf16 v[50:53], v[142:145], v[186:189], v[50:53]
	v_mfma_f32_16x16x32_bf16 v[38:41], v[134:137], v[208:211], v[38:41]
	v_mfma_f32_16x16x32_bf16 v[34:37], v[142:145], v[208:211], v[34:37]
	v_mfma_f32_16x16x32_bf16 v[22:25], v[134:137], v[216:219], v[22:25]
	v_mfma_f32_16x16x32_bf16 v[18:21], v[142:145], v[216:219], v[18:21]
	v_mfma_f32_16x16x32_bf16 v[46:49], v[146:149], v[172:175], v[46:49]
	v_mfma_f32_16x16x32_bf16 v[42:45], v[164:167], v[172:175], v[42:45]
	v_mfma_f32_16x16x32_bf16 v[30:33], v[146:149], v[182:185], v[30:33]
	v_mfma_f32_16x16x32_bf16 v[26:29], v[164:167], v[182:185], v[26:29]
	v_mfma_f32_16x16x32_bf16 v[14:17], v[146:149], v[190:193], v[14:17]
	v_mfma_f32_16x16x32_bf16 v[10:13], v[164:167], v[190:193], v[10:13]
	v_mfma_f32_16x16x32_bf16 v[6:9], v[146:149], v[212:215], v[6:9]
	v_mfma_f32_16x16x32_bf16 v[2:5], v[164:167], v[212:215], v[2:5]
	v_mfma_f32_16x16x32_bf16 v[46:49], v[160:163], v[178:181], v[46:49]
	v_mfma_f32_16x16x32_bf16 v[42:45], v[168:171], v[178:181], v[42:45]
	v_mfma_f32_16x16x32_bf16 v[30:33], v[160:163], v[186:189], v[30:33]
	v_mfma_f32_16x16x32_bf16 v[26:29], v[168:171], v[186:189], v[26:29]
	v_mfma_f32_16x16x32_bf16 v[14:17], v[160:163], v[208:211], v[14:17]
	v_mfma_f32_16x16x32_bf16 v[10:13], v[168:171], v[208:211], v[10:13]
	v_mfma_f32_16x16x32_bf16 v[6:9], v[160:163], v[216:219], v[6:9]
	v_mfma_f32_16x16x32_bf16 v[2:5], v[168:171], v[216:219], v[2:5]
	s_barrier
; #define PG8_STAGE(bufoff, gbase, voff) do { _Pragma("unroll") for (int _i = 0; _i < 2; ++_i) \
;         __builtin_amdgcn_global_load_lds((const unsigned*)((const char*)(gbase) + (voff)[_i]), (PG8_LAS unsigned*)(lds + (bufoff) + ldsw + _i * 8192), 16, 0, 0); } while (0)
; #define PG8_LDA(dst, b, h) do { _Pragma("unroll") for (int m = 0; m < 4; ++m) _Pragma("unroll") for (int k = 0; k < 2; ++k) dst[m][k] = *(const PG8_LAS bf16x8*)(lds + PG8_SA(b, h) + aoff + m * 2048 + k * 1024); } while (0)
; #define PG8_LDB(dst, b, h) do { _Pragma("unroll") for (int n = 0; n < 2; ++n) _Pragma("unroll") for (int k = 0; k < 2; ++k) dst[n][k] = *(const PG8_LAS bf16x8*)(lds + PG8_SB(b, h) + boff + n * 2048 + k * 1024); } while (0)
; #define PG8_MMA(ai, bj, At, Bt) do { __builtin_amdgcn_s_setprio(1); _Pragma("unroll") for (int m = 0; m < 4; ++m) _Pragma("unroll") for (int n = 0; n < 2; ++n) _Pragma("unroll") for (int k = 0; k < 2; ++k) \
;         acc[ai][bj][m][n] = __builtin_amdgcn_mfma_f32_16x16x32_bf16(Bt[n][k], At[m][k], acc[ai][bj][m][n], 0, 0, 0); __builtin_amdgcn_s_setprio(0); } while (0)
; #define PG8_WAIT_V(n) asm volatile("s_waitcnt vmcnt(" #n ")" ::: "memory")
; #define PG8_WAIT_L(n) asm volatile("s_waitcnt lgkmcnt(" #n ")" ::: "memory")
; #define PG8_BAR __builtin_amdgcn_s_barrier()
; #define PG8_SCHED __builtin_amdgcn_sched_barrier(0)
; template <class Epi, class Sched, bool ALIGN_EPI = false, bool SP2 = false>
; __device__ __forceinline__ void gemm_phase(PG8_LAS unsigned char* lds, const Gemm g, const Sched& S, const Epi& E, int wid_in) {
;     ...
;             PG8_LDB(B0, 1, 0); PG8_LDB(B1, 1, 1); PG8_SCHED; PG8_LDA(At, 1, 0); PG8_STAGE(PG8_SA(0, 1), a2 + hstep, voffA);
;             PG8_WAIT_V(8); PG8_WAIT_L(0); PG8_BAR; PG8_MMA(0, 0, At, B0); PG8_MMA(0, 1, At, B1); PG8_BAR; PG8_SCHED;
	s_add_i32 s27, 0, 0x18000
	s_add_i32 s40, 0, 0x1c000
	v_add_u32_e32 v142, s27, v176
	v_add_u32_e32 v168, s40, v176
	ds_read_b128 v[130:133], v142
	ds_read_b128 v[134:137], v142 offset:1024
	ds_read_b128 v[138:141], v142 offset:2048
	ds_read_b128 v[142:145], v142 offset:3072
	ds_read_b128 v[146:149], v168
	ds_read_b128 v[160:163], v168 offset:1024
	ds_read_b128 v[164:167], v168 offset:2048
	ds_read_b128 v[168:171], v168 offset:3072
	s_add_u32 s36, s36, 0x80000
	s_addc_u32 s37, s37, 0
	s_mov_b32 m0, s53
	v_lshl_add_u64 v[228:229], s[36:37], 0, v[150:151]
	ds_read_b128 v[172:175], v177 offset:32768
	ds_read_b128 v[178:181], v177 offset:33792
	ds_read_b128 v[182:185], v177 offset:34816
	ds_read_b128 v[186:189], v177 offset:35840
	ds_read_b128 v[190:193], v177 offset:36864
	ds_read_b128 v[208:211], v177 offset:37888
	ds_read_b128 v[212:215], v177 offset:38912
	ds_read_b128 v[216:219], v177 offset:39936
	global_load_lds_dwordx4 v[228:229], off
	v_lshl_add_u64 v[228:229], s[36:37], 0, v[152:153]
	s_mov_b32 m0, s61
	s_nop 0
	global_load_lds_dwordx4 v[228:229], off
	s_waitcnt vmcnt(8)
	s_waitcnt lgkmcnt(0)
	s_barrier
	s_waitcnt lgkmcnt(0)
	v_mfma_f32_16x16x32_bf16 v[126:129], v[130:133], v[172:175], v[126:129]
	v_mfma_f32_16x16x32_bf16 v[122:125], v[138:141], v[172:175], v[122:125]
	v_mfma_f32_16x16x32_bf16 v[118:121], v[130:133], v[182:185], v[118:121]
	v_mfma_f32_16x16x32_bf16 v[114:117], v[138:141], v[182:185], v[114:117]
	v_mfma_f32_16x16x32_bf16 v[102:105], v[130:133], v[190:193], v[102:105]
	v_mfma_f32_16x16x32_bf16 v[98:101], v[138:141], v[190:193], v[98:101]
	v_mfma_f32_16x16x32_bf16 v[86:89], v[130:133], v[212:215], v[86:89]
	v_mfma_f32_16x16x32_bf16 v[82:85], v[138:141], v[212:215], v[82:85]
	v_mfma_f32_16x16x32_bf16 v[126:129], v[134:137], v[178:181], v[126:129]
	v_mfma_f32_16x16x32_bf16 v[122:125], v[142:145], v[178:181], v[122:125]
	v_mfma_f32_16x16x32_bf16 v[118:121], v[134:137], v[186:189], v[118:121]
	v_mfma_f32_16x16x32_bf16 v[114:117], v[142:145], v[186:189], v[114:117]
	v_mfma_f32_16x16x32_bf16 v[102:105], v[134:137], v[208:211], v[102:105]
	v_mfma_f32_16x16x32_bf16 v[98:101], v[142:145], v[208:211], v[98:101]
	v_mfma_f32_16x16x32_bf16 v[86:89], v[134:137], v[216:219], v[86:89]
	v_mfma_f32_16x16x32_bf16 v[82:85], v[142:145], v[216:219], v[82:85]
	v_mfma_f32_16x16x32_bf16 v[110:113], v[146:149], v[172:175], v[110:113]
	v_mfma_f32_16x16x32_bf16 v[106:109], v[164:167], v[172:175], v[106:109]
	v_mfma_f32_16x16x32_bf16 v[94:97], v[146:149], v[182:185], v[94:97]
	v_mfma_f32_16x16x32_bf16 v[90:93], v[164:167], v[182:185], v[90:93]
	v_mfma_f32_16x16x32_bf16 v[78:81], v[146:149], v[190:193], v[78:81]
	v_mfma_f32_16x16x32_bf16 v[74:77], v[164:167], v[190:193], v[74:77]
	v_mfma_f32_16x16x32_bf16 v[70:73], v[146:149], v[212:215], v[70:73]
	v_mfma_f32_16x16x32_bf16 v[66:69], v[164:167], v[212:215], v[66:69]
	v_mfma_f32_16x16x32_bf16 v[110:113], v[160:163], v[178:181], v[110:113]
	v_mfma_f32_16x16x32_bf16 v[106:109], v[168:171], v[178:181], v[106:109]
	v_mfma_f32_16x16x32_bf16 v[94:97], v[160:163], v[186:189], v[94:97]
	v_mfma_f32_16x16x32_bf16 v[90:93], v[168:171], v[186:189], v[90:93]
	v_mfma_f32_16x16x32_bf16 v[78:81], v[160:163], v[208:211], v[78:81]
	v_mfma_f32_16x16x32_bf16 v[74:77], v[168:171], v[208:211], v[74:77]
	v_mfma_f32_16x16x32_bf16 v[70:73], v[160:163], v[216:219], v[70:73]
	v_mfma_f32_16x16x32_bf16 v[66:69], v[168:171], v[216:219], v[66:69]
	s_barrier
; #define PG8_STAGE(bufoff, gbase, voff) do { _Pragma("unroll") for (int _i = 0; _i < 2; ++_i) \
;         __builtin_amdgcn_global_load_lds((const unsigned*)((const char*)(gbase) + (voff)[_i]), (PG8_LAS unsigned*)(lds + (bufoff) + ldsw + _i * 8192), 16, 0, 0); } while (0)
; #define PG8_LDA(dst, b, h) do { _Pragma("unroll") for (int m = 0; m < 4; ++m) _Pragma("unroll") for (int k = 0; k < 2; ++k) dst[m][k] = *(const PG8_LAS bf16x8*)(lds + PG8_SA(b, h) + aoff + m * 2048 + k * 1024); } while (0)
; #define PG8_MMA(ai, bj, At, Bt) do { __builtin_amdgcn_s_setprio(1); _Pragma("unroll") for (int m = 0; m < 4; ++m) _Pragma("unroll") for (int n = 0; n < 2; ++n) _Pragma("unroll") for (int k = 0; k < 2; ++k) \
;         acc[ai][bj][m][n] = __builtin_amdgcn_mfma_f32_16x16x32_bf16(Bt[n][k], At[m][k], acc[ai][bj][m][n], 0, 0, 0); __builtin_amdgcn_s_setprio(0); } while (0)
; #define PG8_WAIT_V(n) asm volatile("s_waitcnt vmcnt(" #n ")" ::: "memory")
; #define PG8_WAIT_L(n) asm volatile("s_waitcnt lgkmcnt(" #n ")" ::: "memory")
; #define PG8_BAR __builtin_amdgcn_s_barrier()
; #define PG8_SCHED __builtin_amdgcn_sched_barrier(0)
; template <class Epi, class Sched, bool ALIGN_EPI = false, bool SP2 = false>
; __device__ __forceinline__ void gemm_phase(PG8_LAS unsigned char* lds, const Gemm g, const Sched& S, const Epi& E, int wid_in) {
;     ...
;         for (int t = 0; t < nt; t += 2) {
;             const bool last = (t == nt - 2);
;             const char* a1 = cA + (size_t)(t + 1) * kstep;
;             const char* a2 = last ? nA : cA + (size_t)(t + 2) * kstep; const char* b2 = last ? nB : cB + (size_t)(t + 2) * kstep;
;             const char* a3 = a2 + kstep; const char* b3 = b2 + kstep;
;     ...
;             PG8_LDA(At, 1, 1); PG8_STAGE(PG8_SB(1, 0), b3, voffB); PG8_STAGE(PG8_SB(1, 1), b3 + hstep, voffB); PG8_STAGE(PG8_SA(1, 0), a3, voffA);
;             PG8_WAIT_V(8); PG8_WAIT_L(0); PG8_BAR; PG8_MMA(1, 0, At, B0); PG8_MMA(1, 1, At, B1); PG8_BAR; PG8_SCHED;
	s_add_i32 s27, s27, s59
	v_lshl_add_u64 v[220:221], v[220:221], 0, s[94:95]
	s_mov_b32 m0, s27
	ds_read_b128 v[172:175], v177 offset:49152
	ds_read_b128 v[178:181], v177 offset:50176
	ds_read_b128 v[182:185], v177 offset:51200
	ds_read_b128 v[186:189], v177 offset:52224
	ds_read_b128 v[190:193], v177 offset:53248
	ds_read_b128 v[208:211], v177 offset:54272
	ds_read_b128 v[212:215], v177 offset:55296
	ds_read_b128 v[216:219], v177 offset:56320
	global_load_lds_dwordx4 v[220:221], off
	s_add_i32 m0, s27, 0x2000
	s_add_u32 s34, s34, 0x80080
	v_lshl_add_u64 v[220:221], v[222:223], 0, s[94:95]
	s_addc_u32 s35, s35, 0
	s_add_i32 s27, s40, s59
	global_load_lds_dwordx4 v[220:221], off
	v_lshl_add_u64 v[220:221], s[34:35], 0, v[0:1]
	s_mov_b32 m0, s27
	s_nop 0
	global_load_lds_dwordx4 v[220:221], off
	v_lshl_add_u64 v[220:221], s[34:35], 0, v[154:155]
	s_add_i32 m0, s27, 0x2000
	s_nop 0
	global_load_lds_dwordx4 v[220:221], off
	v_lshl_add_u64 v[220:221], v[224:225], 0, s[94:95]
	s_mov_b32 m0, s73
	s_nop 0
	global_load_lds_dwordx4 v[220:221], off
	v_lshl_add_u64 v[220:221], v[226:227], 0, s[94:95]
	s_mov_b32 m0, s80
	s_nop 0
	global_load_lds_dwordx4 v[220:221], off
	s_waitcnt vmcnt(8)
	s_waitcnt lgkmcnt(0)
	s_barrier
	s_waitcnt lgkmcnt(0)
	v_mfma_f32_16x16x32_bf16 v[62:65], v[130:133], v[172:175], v[62:65]
	v_mfma_f32_16x16x32_bf16 v[58:61], v[138:141], v[172:175], v[58:61]
	v_mfma_f32_16x16x32_bf16 v[54:57], v[130:133], v[182:185], v[54:57]
	v_mfma_f32_16x16x32_bf16 v[50:53], v[138:141], v[182:185], v[50:53]
	v_mfma_f32_16x16x32_bf16 v[38:41], v[130:133], v[190:193], v[38:41]
	v_mfma_f32_16x16x32_bf16 v[34:37], v[138:141], v[190:193], v[34:37]
	v_mfma_f32_16x16x32_bf16 v[22:25], v[130:133], v[212:215], v[22:25]
	v_mfma_f32_16x16x32_bf16 v[18:21], v[138:141], v[212:215], v[18:21]
	v_mfma_f32_16x16x32_bf16 v[62:65], v[134:137], v[178:181], v[62:65]
	v_mfma_f32_16x16x32_bf16 v[58:61], v[142:145], v[178:181], v[58:61]
	v_mfma_f32_16x16x32_bf16 v[54:57], v[134:137], v[186:189], v[54:57]
	v_mfma_f32_16x16x32_bf16 v[50:53], v[142:145], v[186:189], v[50:53]
	v_mfma_f32_16x16x32_bf16 v[38:41], v[134:137], v[208:211], v[38:41]
	v_mfma_f32_16x16x32_bf16 v[34:37], v[142:145], v[208:211], v[34:37]
	v_mfma_f32_16x16x32_bf16 v[22:25], v[134:137], v[216:219], v[22:25]
	v_mfma_f32_16x16x32_bf16 v[18:21], v[142:145], v[216:219], v[18:21]
	v_mfma_f32_16x16x32_bf16 v[46:49], v[146:149], v[172:175], v[46:49]
	v_mfma_f32_16x16x32_bf16 v[42:45], v[164:167], v[172:175], v[42:45]
	v_mfma_f32_16x16x32_bf16 v[30:33], v[146:149], v[182:185], v[30:33]
	v_mfma_f32_16x16x32_bf16 v[26:29], v[164:167], v[182:185], v[26:29]
	v_mfma_f32_16x16x32_bf16 v[14:17], v[146:149], v[190:193], v[14:17]
	v_mfma_f32_16x16x32_bf16 v[10:13], v[164:167], v[190:193], v[10:13]
	v_mfma_f32_16x16x32_bf16 v[6:9], v[146:149], v[212:215], v[6:9]
	v_mfma_f32_16x16x32_bf16 v[2:5], v[164:167], v[212:215], v[2:5]
	v_mfma_f32_16x16x32_bf16 v[46:49], v[160:163], v[178:181], v[46:49]
	v_mfma_f32_16x16x32_bf16 v[42:45], v[168:171], v[178:181], v[42:45]
	v_mfma_f32_16x16x32_bf16 v[30:33], v[160:163], v[186:189], v[30:33]
	v_mfma_f32_16x16x32_bf16 v[26:29], v[168:171], v[186:189], v[26:29]
	v_mfma_f32_16x16x32_bf16 v[14:17], v[160:163], v[208:211], v[14:17]
	v_mfma_f32_16x16x32_bf16 v[10:13], v[168:171], v[208:211], v[10:13]
	v_mfma_f32_16x16x32_bf16 v[6:9], v[160:163], v[216:219], v[6:9]
	v_mfma_f32_16x16x32_bf16 v[2:5], v[168:171], v[216:219], v[2:5]
	s_add_u32 s19, s19, 0x100
	s_addc_u32 s21, s21, 0
	s_add_u32 s30, s30, 0x100
	s_addc_u32 s31, s31, 0
	s_cmp_ge_i32 s56, s90
	s_mov_b32 s27, s56
	s_cbranch_scc1 .Lrot_exit_3
	s_add_i32 s56, s27, 2
	s_add_u32 s34, s30, 0xfff80080
	s_addc_u32 s35, s31, -1
	s_add_i32 s40, 0, 0x10000
	s_cmp_eq_u32 s17, s27
	s_cselect_b32 s37, s23, s35
	s_cselect_b32 s36, s22, s34
	s_cselect_b32 s35, s25, s21
	s_cselect_b32 s34, s24, s19
	s_add_i32 s27, 0, 0x14000
	v_add_u32_e32 v142, s40, v176
	v_add_u32_e32 v168, s27, v176
	s_barrier
	s_branch .Lrot_3

; #define PG8_STAGE(bufoff, gbase, voff) do { _Pragma("unroll") for (int _i = 0; _i < 2; ++_i) \
;         __builtin_amdgcn_global_load_lds((const unsigned*)((const char*)(gbase) + (voff)[_i]), (PG8_LAS unsigned*)(lds + (bufoff) + ldsw + _i * 8192), 16, 0, 0); } while (0)
; #define PG8_LDA(dst, b, h) do { _Pragma("unroll") for (int m = 0; m < 4; ++m) _Pragma("unroll") for (int k = 0; k < 2; ++k) dst[m][k] = *(const PG8_LAS bf16x8*)(lds + PG8_SA(b, h) + aoff + m * 2048 + k * 1024); } while (0)
; #define PG8_LDB(dst, b, h) do { _Pragma("unroll") for (int n = 0; n < 2; ++n) _Pragma("unroll") for (int k = 0; k < 2; ++k) dst[n][k] = *(const PG8_LAS bf16x8*)(lds + PG8_SB(b, h) + boff + n * 2048 + k * 1024); } while (0)
; #define PG8_MMA(ai, bj, At, Bt) do { __builtin_amdgcn_s_setprio(1); _Pragma("unroll") for (int m = 0; m < 4; ++m) _Pragma("unroll") for (int n = 0; n < 2; ++n) _Pragma("unroll") for (int k = 0; k < 2; ++k) \
;         acc[ai][bj][m][n] = __builtin_amdgcn_mfma_f32_16x16x32_bf16(Bt[n][k], At[m][k], acc[ai][bj][m][n], 0, 0, 0); __builtin_amdgcn_s_setprio(0); } while (0)
; #define PG8_WAIT_V(n) asm volatile("s_waitcnt vmcnt(" #n ")" ::: "memory")
; #define PG8_WAIT_L(n) asm volatile("s_waitcnt lgkmcnt(" #n ")" ::: "memory")
; #define PG8_BAR __builtin_amdgcn_s_barrier()
; #define PG8_SCHED __builtin_amdgcn_sched_barrier(0)
; template <class Epi, class Sched, bool ALIGN_EPI = false, bool SP2 = false>
; __device__ __forceinline__ void gemm_phase(PG8_LAS unsigned char* lds, const Gemm g, const Sched& S, const Epi& E, int wid_in) {
;     ...
;             PG8_LDB(B0, 0, 0); PG8_LDB(B1, 0, 1); PG8_SCHED; PG8_LDA(At, 0, 0); PG8_STAGE(PG8_SA(1, 1), a1 + hstep, voffA);
;             PG8_WAIT_V(8); PG8_WAIT_L(0); PG8_BAR; PG8_MMA(0, 0, At, B0); PG8_MMA(0, 1, At, B1); PG8_BAR; PG8_SCHED;
;             PG8_LDA(At, 0, 1); PG8_STAGE(PG8_SB(0, 0), b2, voffB); PG8_STAGE(PG8_SB(0, 1), b2 + hstep, voffB); PG8_STAGE(PG8_SA(0, 0), a2, voffA);
;             PG8_WAIT_V(8); PG8_WAIT_L(0); PG8_BAR; PG8_MMA(1, 0, At, B0); PG8_MMA(1, 1, At, B1); PG8_BAR; PG8_SCHED;
.Lrot_4:
	ds_read_b128 v[144:147], v140
	ds_read_b128 v[148:151], v140 offset:1024
	ds_read_b128 v[152:155], v140 offset:2048
	ds_read_b128 v[156:159], v140 offset:3072
	v_add_u32_e32 v140, s42, v142
	ds_read_b128 v[160:163], v140
	ds_read_b128 v[164:167], v140 offset:1024
	ds_read_b128 v[168:171], v140 offset:2048
	ds_read_b128 v[172:175], v140 offset:3072
	v_lshl_add_u64 v[140:141], s[24:25], 0, v[138:139]
	s_add_i32 m0, s34, 0xc000
	ds_read_b128 v[176:179], v143
	ds_read_b128 v[180:183], v143 offset:1024
	ds_read_b128 v[184:187], v143 offset:2048
	ds_read_b128 v[188:191], v143 offset:3072
	ds_read_b128 v[208:211], v143 offset:4096
	ds_read_b128 v[212:215], v143 offset:5120
	ds_read_b128 v[216:219], v143 offset:6144
	ds_read_b128 v[220:223], v143 offset:7168
	global_load_lds_dwordx4 v[140:141], off
	v_lshl_add_u64 v[140:141], s[24:25], 0, v[136:137]
	s_add_i32 m0, s34, 0xe000
	s_nop 0
	global_load_lds_dwordx4 v[140:141], off
	s_waitcnt vmcnt(8)
	s_waitcnt lgkmcnt(0)
	s_barrier
	s_waitcnt lgkmcnt(0)
	v_mfma_f32_16x16x32_bf16 v[126:129], v[144:147], v[176:179], v[126:129]
	v_mfma_f32_16x16x32_bf16 v[122:125], v[152:155], v[176:179], v[122:125]
	v_mfma_f32_16x16x32_bf16 v[110:113], v[144:147], v[184:187], v[110:113]
	v_mfma_f32_16x16x32_bf16 v[106:109], v[152:155], v[184:187], v[106:109]
	v_mfma_f32_16x16x32_bf16 v[94:97], v[144:147], v[208:211], v[94:97]
	v_mfma_f32_16x16x32_bf16 v[90:93], v[152:155], v[208:211], v[90:93]
	v_mfma_f32_16x16x32_bf16 v[78:81], v[144:147], v[216:219], v[78:81]
	v_mfma_f32_16x16x32_bf16 v[74:77], v[152:155], v[216:219], v[74:77]
	v_mfma_f32_16x16x32_bf16 v[126:129], v[148:151], v[180:183], v[126:129]
	v_mfma_f32_16x16x32_bf16 v[122:125], v[156:159], v[180:183], v[122:125]
	v_mfma_f32_16x16x32_bf16 v[110:113], v[148:151], v[188:191], v[110:113]
	v_mfma_f32_16x16x32_bf16 v[106:109], v[156:159], v[188:191], v[106:109]
	v_mfma_f32_16x16x32_bf16 v[94:97], v[148:151], v[212:215], v[94:97]
	v_mfma_f32_16x16x32_bf16 v[90:93], v[156:159], v[212:215], v[90:93]
	v_mfma_f32_16x16x32_bf16 v[78:81], v[148:151], v[220:223], v[78:81]
	v_mfma_f32_16x16x32_bf16 v[74:77], v[156:159], v[220:223], v[74:77]
	v_mfma_f32_16x16x32_bf16 v[118:121], v[160:163], v[176:179], v[118:121]
	v_mfma_f32_16x16x32_bf16 v[114:117], v[168:171], v[176:179], v[114:117]
	v_mfma_f32_16x16x32_bf16 v[102:105], v[160:163], v[184:187], v[102:105]
	v_mfma_f32_16x16x32_bf16 v[98:101], v[168:171], v[184:187], v[98:101]
	v_mfma_f32_16x16x32_bf16 v[86:89], v[160:163], v[208:211], v[86:89]
	v_mfma_f32_16x16x32_bf16 v[82:85], v[168:171], v[208:211], v[82:85]
	v_mfma_f32_16x16x32_bf16 v[70:73], v[160:163], v[216:219], v[70:73]
	v_mfma_f32_16x16x32_bf16 v[66:69], v[168:171], v[216:219], v[66:69]
	v_mfma_f32_16x16x32_bf16 v[118:121], v[164:167], v[180:183], v[118:121]
	v_mfma_f32_16x16x32_bf16 v[114:117], v[172:175], v[180:183], v[114:117]
	v_mfma_f32_16x16x32_bf16 v[102:105], v[164:167], v[188:191], v[102:105]
	v_mfma_f32_16x16x32_bf16 v[98:101], v[172:175], v[188:191], v[98:101]
	v_mfma_f32_16x16x32_bf16 v[86:89], v[164:167], v[212:215], v[86:89]
	v_mfma_f32_16x16x32_bf16 v[82:85], v[172:175], v[212:215], v[82:85]
	v_mfma_f32_16x16x32_bf16 v[70:73], v[164:167], v[220:223], v[70:73]
	v_mfma_f32_16x16x32_bf16 v[66:69], v[172:175], v[220:223], v[66:69]
	s_barrier
	s_add_i32 s40, s40, s59
	v_lshl_add_u64 v[140:141], s[26:27], 0, v[0:1]
	s_mov_b32 m0, s40
	ds_read_b128 v[176:179], v143 offset:16384
	ds_read_b128 v[180:183], v143 offset:17408
	ds_read_b128 v[184:187], v143 offset:18432
	ds_read_b128 v[188:191], v143 offset:19456
	ds_read_b128 v[208:211], v143 offset:20480
	ds_read_b128 v[212:215], v143 offset:21504
	ds_read_b128 v[216:219], v143 offset:22528
	ds_read_b128 v[220:223], v143 offset:23552
	global_load_lds_dwordx4 v[140:141], off
	s_add_i32 m0, s40, 0x2000
	s_add_u32 s40, s26, 0x80000
	v_lshl_add_u64 v[192:193], s[26:27], 0, v[130:131]
	s_addc_u32 s41, s27, 0
	s_add_i32 s42, s42, s59
	global_load_lds_dwordx4 v[192:193], off
	v_lshl_add_u64 v[224:225], s[40:41], 0, v[0:1]
	s_mov_b32 m0, s42
	v_lshl_add_u64 v[226:227], s[28:29], 0, v[132:133]
	global_load_lds_dwordx4 v[224:225], off
	v_lshl_add_u64 v[224:225], s[40:41], 0, v[130:131]
	s_add_i32 m0, s42, 0x2000
	s_nop 0
	global_load_lds_dwordx4 v[224:225], off
	v_lshl_add_u64 v[224:225], s[28:29], 0, v[134:135]
	s_mov_b32 m0, s34
	s_nop 0
	global_load_lds_dwordx4 v[224:225], off
	s_mov_b32 m0, s35
	s_nop 0
	global_load_lds_dwordx4 v[226:227], off
	s_waitcnt vmcnt(8)
	s_waitcnt lgkmcnt(0)
	s_barrier
	s_waitcnt lgkmcnt(0)
	v_mfma_f32_16x16x32_bf16 v[62:65], v[144:147], v[176:179], v[62:65]
	v_mfma_f32_16x16x32_bf16 v[58:61], v[152:155], v[176:179], v[58:61]
	v_mfma_f32_16x16x32_bf16 v[46:49], v[144:147], v[184:187], v[46:49]
	v_mfma_f32_16x16x32_bf16 v[42:45], v[152:155], v[184:187], v[42:45]
	v_mfma_f32_16x16x32_bf16 v[30:33], v[144:147], v[208:211], v[30:33]
	v_mfma_f32_16x16x32_bf16 v[26:29], v[152:155], v[208:211], v[26:29]
	v_mfma_f32_16x16x32_bf16 v[14:17], v[144:147], v[216:219], v[14:17]
	v_mfma_f32_16x16x32_bf16 v[10:13], v[152:155], v[216:219], v[10:13]
	v_mfma_f32_16x16x32_bf16 v[62:65], v[148:151], v[180:183], v[62:65]
	v_mfma_f32_16x16x32_bf16 v[58:61], v[156:159], v[180:183], v[58:61]
	v_mfma_f32_16x16x32_bf16 v[46:49], v[148:151], v[188:191], v[46:49]
	v_mfma_f32_16x16x32_bf16 v[42:45], v[156:159], v[188:191], v[42:45]
	v_mfma_f32_16x16x32_bf16 v[30:33], v[148:151], v[212:215], v[30:33]
	v_mfma_f32_16x16x32_bf16 v[26:29], v[156:159], v[212:215], v[26:29]
	v_mfma_f32_16x16x32_bf16 v[14:17], v[148:151], v[220:223], v[14:17]
	v_mfma_f32_16x16x32_bf16 v[10:13], v[156:159], v[220:223], v[10:13]
	v_mfma_f32_16x16x32_bf16 v[54:57], v[160:163], v[176:179], v[54:57]
	v_mfma_f32_16x16x32_bf16 v[50:53], v[168:171], v[176:179], v[50:53]
	v_mfma_f32_16x16x32_bf16 v[38:41], v[160:163], v[184:187], v[38:41]
	v_mfma_f32_16x16x32_bf16 v[34:37], v[168:171], v[184:187], v[34:37]
	v_mfma_f32_16x16x32_bf16 v[22:25], v[160:163], v[208:211], v[22:25]
	v_mfma_f32_16x16x32_bf16 v[18:21], v[168:171], v[208:211], v[18:21]
	v_mfma_f32_16x16x32_bf16 v[6:9], v[160:163], v[216:219], v[6:9]
	v_mfma_f32_16x16x32_bf16 v[2:5], v[168:171], v[216:219], v[2:5]
	v_mfma_f32_16x16x32_bf16 v[54:57], v[164:167], v[180:183], v[54:57]
	v_mfma_f32_16x16x32_bf16 v[50:53], v[172:175], v[180:183], v[50:53]
	v_mfma_f32_16x16x32_bf16 v[38:41], v[164:167], v[188:191], v[38:41]
	v_mfma_f32_16x16x32_bf16 v[34:37], v[172:175], v[188:191], v[34:37]
	v_mfma_f32_16x16x32_bf16 v[22:25], v[164:167], v[212:215], v[22:25]
	v_mfma_f32_16x16x32_bf16 v[18:21], v[172:175], v[212:215], v[18:21]
	v_mfma_f32_16x16x32_bf16 v[6:9], v[164:167], v[220:223], v[6:9]
	v_mfma_f32_16x16x32_bf16 v[2:5], v[172:175], v[220:223], v[2:5]
	s_barrier
; #define PG8_STAGE(bufoff, gbase, voff) do { _Pragma("unroll") for (int _i = 0; _i < 2; ++_i) \
;         __builtin_amdgcn_global_load_lds((const unsigned*)((const char*)(gbase) + (voff)[_i]), (PG8_LAS unsigned*)(lds + (bufoff) + ldsw + _i * 8192), 16, 0, 0); } while (0)
; #define PG8_LDA(dst, b, h) do { _Pragma("unroll") for (int m = 0; m < 4; ++m) _Pragma("unroll") for (int k = 0; k < 2; ++k) dst[m][k] = *(const PG8_LAS bf16x8*)(lds + PG8_SA(b, h) + aoff + m * 2048 + k * 1024); } while (0)
; #define PG8_LDB(dst, b, h) do { _Pragma("unroll") for (int n = 0; n < 2; ++n) _Pragma("unroll") for (int k = 0; k < 2; ++k) dst[n][k] = *(const PG8_LAS bf16x8*)(lds + PG8_SB(b, h) + boff + n * 2048 + k * 1024); } while (0)
; #define PG8_MMA(ai, bj, At, Bt) do { __builtin_amdgcn_s_setprio(1); _Pragma("unroll") for (int m = 0; m < 4; ++m) _Pragma("unroll") for (int n = 0; n < 2; ++n) _Pragma("unroll") for (int k = 0; k < 2; ++k) \
;         acc[ai][bj][m][n] = __builtin_amdgcn_mfma_f32_16x16x32_bf16(Bt[n][k], At[m][k], acc[ai][bj][m][n], 0, 0, 0); __builtin_amdgcn_s_setprio(0); } while (0)
; #define PG8_WAIT_V(n) asm volatile("s_waitcnt vmcnt(" #n ")" ::: "memory")
; #define PG8_WAIT_L(n) asm volatile("s_waitcnt lgkmcnt(" #n ")" ::: "memory")
; #define PG8_BAR __builtin_amdgcn_s_barrier()
; #define PG8_SCHED __builtin_amdgcn_sched_barrier(0)
; template <class Epi, class Sched, bool ALIGN_EPI = false, bool SP2 = false>
; __device__ __forceinline__ void gemm_phase(PG8_LAS unsigned char* lds, const Gemm g, const Sched& S, const Epi& E, int wid_in) {
;     ...
;             PG8_LDB(B0, 1, 0); PG8_LDB(B1, 1, 1); PG8_SCHED; PG8_LDA(At, 1, 0); PG8_STAGE(PG8_SA(0, 1), a2 + hstep, voffA);
;             PG8_WAIT_V(8); PG8_WAIT_L(0); PG8_BAR; PG8_MMA(0, 0, At, B0); PG8_MMA(0, 1, At, B1); PG8_BAR; PG8_SCHED;
	s_add_i32 s40, 0, 0x18000
	s_add_i32 s41, 0, 0x1c000
	v_add_u32_e32 v156, s40, v142
	v_add_u32_e32 v172, s41, v142
	ds_read_b128 v[144:147], v156
	ds_read_b128 v[148:151], v156 offset:1024
	ds_read_b128 v[152:155], v156 offset:2048
	ds_read_b128 v[156:159], v156 offset:3072
	ds_read_b128 v[160:163], v172
	ds_read_b128 v[164:167], v172 offset:1024
	ds_read_b128 v[168:171], v172 offset:2048
	ds_read_b128 v[172:175], v172 offset:3072
	s_add_u32 s28, s28, 0x80000
	s_addc_u32 s29, s29, 0
	s_mov_b32 m0, s36
	v_lshl_add_u64 v[228:229], s[28:29], 0, v[134:135]
	ds_read_b128 v[176:179], v143 offset:32768
	ds_read_b128 v[180:183], v143 offset:33792
	ds_read_b128 v[184:187], v143 offset:34816
	ds_read_b128 v[188:191], v143 offset:35840
	ds_read_b128 v[208:211], v143 offset:36864
	ds_read_b128 v[212:215], v143 offset:37888
	ds_read_b128 v[216:219], v143 offset:38912
	ds_read_b128 v[220:223], v143 offset:39936
	global_load_lds_dwordx4 v[228:229], off
	v_lshl_add_u64 v[228:229], s[28:29], 0, v[132:133]
	s_mov_b32 m0, s37
	s_nop 0
	global_load_lds_dwordx4 v[228:229], off
	s_waitcnt vmcnt(8)
	s_waitcnt lgkmcnt(0)
	s_barrier
	s_waitcnt lgkmcnt(0)
	v_mfma_f32_16x16x32_bf16 v[126:129], v[144:147], v[176:179], v[126:129]
	v_mfma_f32_16x16x32_bf16 v[122:125], v[152:155], v[176:179], v[122:125]
	v_mfma_f32_16x16x32_bf16 v[110:113], v[144:147], v[184:187], v[110:113]
	v_mfma_f32_16x16x32_bf16 v[106:109], v[152:155], v[184:187], v[106:109]
	v_mfma_f32_16x16x32_bf16 v[94:97], v[144:147], v[208:211], v[94:97]
	v_mfma_f32_16x16x32_bf16 v[90:93], v[152:155], v[208:211], v[90:93]
	v_mfma_f32_16x16x32_bf16 v[78:81], v[144:147], v[216:219], v[78:81]
	v_mfma_f32_16x16x32_bf16 v[74:77], v[152:155], v[216:219], v[74:77]
	v_mfma_f32_16x16x32_bf16 v[126:129], v[148:151], v[180:183], v[126:129]
	v_mfma_f32_16x16x32_bf16 v[122:125], v[156:159], v[180:183], v[122:125]
	v_mfma_f32_16x16x32_bf16 v[110:113], v[148:151], v[188:191], v[110:113]
	v_mfma_f32_16x16x32_bf16 v[106:109], v[156:159], v[188:191], v[106:109]
	v_mfma_f32_16x16x32_bf16 v[94:97], v[148:151], v[212:215], v[94:97]
	v_mfma_f32_16x16x32_bf16 v[90:93], v[156:159], v[212:215], v[90:93]
	v_mfma_f32_16x16x32_bf16 v[78:81], v[148:151], v[220:223], v[78:81]
	v_mfma_f32_16x16x32_bf16 v[74:77], v[156:159], v[220:223], v[74:77]
	v_mfma_f32_16x16x32_bf16 v[118:121], v[160:163], v[176:179], v[118:121]
	v_mfma_f32_16x16x32_bf16 v[114:117], v[168:171], v[176:179], v[114:117]
	v_mfma_f32_16x16x32_bf16 v[102:105], v[160:163], v[184:187], v[102:105]
	v_mfma_f32_16x16x32_bf16 v[98:101], v[168:171], v[184:187], v[98:101]
	v_mfma_f32_16x16x32_bf16 v[86:89], v[160:163], v[208:211], v[86:89]
	v_mfma_f32_16x16x32_bf16 v[82:85], v[168:171], v[208:211], v[82:85]
	v_mfma_f32_16x16x32_bf16 v[70:73], v[160:163], v[216:219], v[70:73]
	v_mfma_f32_16x16x32_bf16 v[66:69], v[168:171], v[216:219], v[66:69]
	v_mfma_f32_16x16x32_bf16 v[118:121], v[164:167], v[180:183], v[118:121]
	v_mfma_f32_16x16x32_bf16 v[114:117], v[172:175], v[180:183], v[114:117]
	v_mfma_f32_16x16x32_bf16 v[102:105], v[164:167], v[188:191], v[102:105]
	v_mfma_f32_16x16x32_bf16 v[98:101], v[172:175], v[188:191], v[98:101]
	v_mfma_f32_16x16x32_bf16 v[86:89], v[164:167], v[212:215], v[86:89]
	v_mfma_f32_16x16x32_bf16 v[82:85], v[172:175], v[212:215], v[82:85]
	v_mfma_f32_16x16x32_bf16 v[70:73], v[164:167], v[220:223], v[70:73]
	v_mfma_f32_16x16x32_bf16 v[66:69], v[172:175], v[220:223], v[66:69]
	s_barrier
; #define PG8_STAGE(bufoff, gbase, voff) do { _Pragma("unroll") for (int _i = 0; _i < 2; ++_i) \
;         __builtin_amdgcn_global_load_lds((const unsigned*)((const char*)(gbase) + (voff)[_i]), (PG8_LAS unsigned*)(lds + (bufoff) + ldsw + _i * 8192), 16, 0, 0); } while (0)
; #define PG8_LDA(dst, b, h) do { _Pragma("unroll") for (int m = 0; m < 4; ++m) _Pragma("unroll") for (int k = 0; k < 2; ++k) dst[m][k] = *(const PG8_LAS bf16x8*)(lds + PG8_SA(b, h) + aoff + m * 2048 + k * 1024); } while (0)
; #define PG8_MMA(ai, bj, At, Bt) do { __builtin_amdgcn_s_setprio(1); _Pragma("unroll") for (int m = 0; m < 4; ++m) _Pragma("unroll") for (int n = 0; n < 2; ++n) _Pragma("unroll") for (int k = 0; k < 2; ++k) \
;         acc[ai][bj][m][n] = __builtin_amdgcn_mfma_f32_16x16x32_bf16(Bt[n][k], At[m][k], acc[ai][bj][m][n], 0, 0, 0); __builtin_amdgcn_s_setprio(0); } while (0)
; #define PG8_WAIT_V(n) asm volatile("s_waitcnt vmcnt(" #n ")" ::: "memory")
; #define PG8_WAIT_L(n) asm volatile("s_waitcnt lgkmcnt(" #n ")" ::: "memory")
; #define PG8_BAR __builtin_amdgcn_s_barrier()
; #define PG8_SCHED __builtin_amdgcn_sched_barrier(0)
; template <class Epi, class Sched, bool ALIGN_EPI = false, bool SP2 = false>
; __device__ __forceinline__ void gemm_phase(PG8_LAS unsigned char* lds, const Gemm g, const Sched& S, const Epi& E, int wid_in) {
;     ...
;         for (int t = 0; t < nt; t += 2) {
;             const bool last = (t == nt - 2);
;             const char* a1 = cA + (size_t)(t + 1) * kstep;
;             const char* a2 = last ? nA : cA + (size_t)(t + 2) * kstep; const char* b2 = last ? nB : cB + (size_t)(t + 2) * kstep;
;             const char* a3 = a2 + kstep; const char* b3 = b2 + kstep;
;     ...
;             PG8_LDA(At, 1, 1); PG8_STAGE(PG8_SB(1, 0), b3, voffB); PG8_STAGE(PG8_SB(1, 1), b3 + hstep, voffB); PG8_STAGE(PG8_SA(1, 0), a3, voffA);
;             PG8_WAIT_V(8); PG8_WAIT_L(0); PG8_BAR; PG8_MMA(1, 0, At, B0); PG8_MMA(1, 1, At, B1); PG8_BAR; PG8_SCHED;
	s_add_i32 s28, s40, s59
	v_lshl_add_u64 v[140:141], v[140:141], 0, s[94:95]
	s_mov_b32 m0, s28
	ds_read_b128 v[176:179], v143 offset:49152
	ds_read_b128 v[180:183], v143 offset:50176
	ds_read_b128 v[184:187], v143 offset:51200
	ds_read_b128 v[188:191], v143 offset:52224
	ds_read_b128 v[208:211], v143 offset:53248
	ds_read_b128 v[212:215], v143 offset:54272
	ds_read_b128 v[216:219], v143 offset:55296
	ds_read_b128 v[220:223], v143 offset:56320
	global_load_lds_dwordx4 v[140:141], off
	s_add_i32 m0, s28, 0x2000
	s_add_u32 s26, s26, 0x80080
	v_lshl_add_u64 v[140:141], v[192:193], 0, s[94:95]
	s_addc_u32 s27, s27, 0
	s_add_i32 s28, s41, s59
	global_load_lds_dwordx4 v[140:141], off
	v_lshl_add_u64 v[140:141], s[26:27], 0, v[0:1]
	s_mov_b32 m0, s28
	s_nop 0
	global_load_lds_dwordx4 v[140:141], off
	v_lshl_add_u64 v[140:141], s[26:27], 0, v[130:131]
	s_add_i32 m0, s28, 0x2000
	s_nop 0
	global_load_lds_dwordx4 v[140:141], off
	v_lshl_add_u64 v[140:141], v[224:225], 0, s[94:95]
	s_mov_b32 m0, s48
	s_nop 0
	global_load_lds_dwordx4 v[140:141], off
	v_lshl_add_u64 v[140:141], v[226:227], 0, s[94:95]
	s_mov_b32 m0, s52
	s_nop 0
	global_load_lds_dwordx4 v[140:141], off
	s_waitcnt vmcnt(8)
	s_waitcnt lgkmcnt(0)
	s_barrier
	s_waitcnt lgkmcnt(0)
	v_mfma_f32_16x16x32_bf16 v[62:65], v[144:147], v[176:179], v[62:65]
	v_mfma_f32_16x16x32_bf16 v[58:61], v[152:155], v[176:179], v[58:61]
	v_mfma_f32_16x16x32_bf16 v[46:49], v[144:147], v[184:187], v[46:49]
	v_mfma_f32_16x16x32_bf16 v[42:45], v[152:155], v[184:187], v[42:45]
	v_mfma_f32_16x16x32_bf16 v[30:33], v[144:147], v[208:211], v[30:33]
	v_mfma_f32_16x16x32_bf16 v[26:29], v[152:155], v[208:211], v[26:29]
	v_mfma_f32_16x16x32_bf16 v[14:17], v[144:147], v[216:219], v[14:17]
	v_mfma_f32_16x16x32_bf16 v[10:13], v[152:155], v[216:219], v[10:13]
	v_mfma_f32_16x16x32_bf16 v[62:65], v[148:151], v[180:183], v[62:65]
	v_mfma_f32_16x16x32_bf16 v[58:61], v[156:159], v[180:183], v[58:61]
	v_mfma_f32_16x16x32_bf16 v[46:49], v[148:151], v[188:191], v[46:49]
	v_mfma_f32_16x16x32_bf16 v[42:45], v[156:159], v[188:191], v[42:45]
	v_mfma_f32_16x16x32_bf16 v[30:33], v[148:151], v[212:215], v[30:33]
	v_mfma_f32_16x16x32_bf16 v[26:29], v[156:159], v[212:215], v[26:29]
	v_mfma_f32_16x16x32_bf16 v[14:17], v[148:151], v[220:223], v[14:17]
	v_mfma_f32_16x16x32_bf16 v[10:13], v[156:159], v[220:223], v[10:13]
	v_mfma_f32_16x16x32_bf16 v[54:57], v[160:163], v[176:179], v[54:57]
	v_mfma_f32_16x16x32_bf16 v[50:53], v[168:171], v[176:179], v[50:53]
	v_mfma_f32_16x16x32_bf16 v[38:41], v[160:163], v[184:187], v[38:41]
	v_mfma_f32_16x16x32_bf16 v[34:37], v[168:171], v[184:187], v[34:37]
	v_mfma_f32_16x16x32_bf16 v[22:25], v[160:163], v[208:211], v[22:25]
	v_mfma_f32_16x16x32_bf16 v[18:21], v[168:171], v[208:211], v[18:21]
	v_mfma_f32_16x16x32_bf16 v[6:9], v[160:163], v[216:219], v[6:9]
	v_mfma_f32_16x16x32_bf16 v[2:5], v[168:171], v[216:219], v[2:5]
	v_mfma_f32_16x16x32_bf16 v[54:57], v[164:167], v[180:183], v[54:57]
	v_mfma_f32_16x16x32_bf16 v[50:53], v[172:175], v[180:183], v[50:53]
	v_mfma_f32_16x16x32_bf16 v[38:41], v[164:167], v[188:191], v[38:41]
	v_mfma_f32_16x16x32_bf16 v[34:37], v[172:175], v[188:191], v[34:37]
	v_mfma_f32_16x16x32_bf16 v[22:25], v[164:167], v[212:215], v[22:25]
	v_mfma_f32_16x16x32_bf16 v[18:21], v[172:175], v[212:215], v[18:21]
	v_mfma_f32_16x16x32_bf16 v[6:9], v[164:167], v[220:223], v[6:9]
	v_mfma_f32_16x16x32_bf16 v[2:5], v[172:175], v[220:223], v[2:5]
	s_add_i32 s73, s73, 2
	s_add_u32 s72, s72, 0x100
	s_addc_u32 s63, s63, 0
	s_add_u32 s24, s24, 0x100
	s_addc_u32 s25, s25, 0
	s_cmp_gt_u32 s73, 29
	s_cbranch_scc1 .Lrot_exit_4
	s_add_u32 s26, s24, 0xfff80080
	s_addc_u32 s27, s25, -1
	s_add_i32 s40, 0, 0x10000
	s_cmp_eq_u32 s73, 28
	s_cselect_b32 s29, s19, s27
	s_cselect_b32 s28, s64, s26
	v_add_u32_e32 v140, s40, v142
	s_cselect_b32 s27, s17, s63
	s_cselect_b32 s26, s65, s72
	s_add_i32 s42, 0, 0x14000
	s_barrier
	s_branch .Lrot_4

; #define PG8_STAGE(bufoff, gbase, voff) do { _Pragma("unroll") for (int _i = 0; _i < 2; ++_i) \
;         __builtin_amdgcn_global_load_lds((const unsigned*)((const char*)(gbase) + (voff)[_i]), (PG8_LAS unsigned*)(lds + (bufoff) + ldsw + _i * 8192), 16, 0, 0); } while (0)
; #define PG8_LDA(dst, b, h) do { _Pragma("unroll") for (int m = 0; m < 4; ++m) _Pragma("unroll") for (int k = 0; k < 2; ++k) dst[m][k] = *(const PG8_LAS bf16x8*)(lds + PG8_SA(b, h) + aoff + m * 2048 + k * 1024); } while (0)
; #define PG8_LDB(dst, b, h) do { _Pragma("unroll") for (int n = 0; n < 2; ++n) _Pragma("unroll") for (int k = 0; k < 2; ++k) dst[n][k] = *(const PG8_LAS bf16x8*)(lds + PG8_SB(b, h) + boff + n * 2048 + k * 1024); } while (0)
; #define PG8_MMA(ai, bj, At, Bt) do { __builtin_amdgcn_s_setprio(1); _Pragma("unroll") for (int m = 0; m < 4; ++m) _Pragma("unroll") for (int n = 0; n < 2; ++n) _Pragma("unroll") for (int k = 0; k < 2; ++k) \
;         acc[ai][bj][m][n] = __builtin_amdgcn_mfma_f32_16x16x32_bf16(Bt[n][k], At[m][k], acc[ai][bj][m][n], 0, 0, 0); __builtin_amdgcn_s_setprio(0); } while (0)
; #define PG8_WAIT_V(n) asm volatile("s_waitcnt vmcnt(" #n ")" ::: "memory")
; #define PG8_WAIT_L(n) asm volatile("s_waitcnt lgkmcnt(" #n ")" ::: "memory")
; #define PG8_BAR __builtin_amdgcn_s_barrier()
; #define PG8_SCHED __builtin_amdgcn_sched_barrier(0)
; template <class Epi, class Sched, bool ALIGN_EPI = false, bool SP2 = false>
; __device__ __forceinline__ void gemm_phase(PG8_LAS unsigned char* lds, const Gemm g, const Sched& S, const Epi& E, int wid_in) {
;     ...
;             PG8_LDB(B0, 0, 0); PG8_LDB(B1, 0, 1); PG8_SCHED; PG8_LDA(At, 0, 0); PG8_STAGE(PG8_SA(1, 1), a1 + hstep, voffA);
;             PG8_WAIT_V(8); PG8_WAIT_L(0); PG8_BAR; PG8_MMA(0, 0, At, B0); PG8_MMA(0, 1, At, B1); PG8_BAR; PG8_SCHED;
;             PG8_LDA(At, 0, 1); PG8_STAGE(PG8_SB(0, 0), b2, voffB); PG8_STAGE(PG8_SB(0, 1), b2 + hstep, voffB); PG8_STAGE(PG8_SA(0, 0), a2, voffA);
;             PG8_WAIT_V(8); PG8_WAIT_L(0); PG8_BAR; PG8_MMA(1, 0, At, B0); PG8_MMA(1, 1, At, B1); PG8_BAR; PG8_SCHED;
.Lrot_5:
	ds_read_b128 v[130:133], v142
	ds_read_b128 v[134:137], v142 offset:1024
	ds_read_b128 v[138:141], v142 offset:2048
	ds_read_b128 v[142:145], v142 offset:3072
	ds_read_b128 v[146:149], v168
	ds_read_b128 v[160:163], v168 offset:1024
	ds_read_b128 v[164:167], v168 offset:2048
	ds_read_b128 v[168:171], v168 offset:3072
	v_lshl_add_u64 v[220:221], s[30:31], 0, v[158:159]
	s_add_i32 m0, s29, 0xc000
	ds_read_b128 v[172:175], v177
	ds_read_b128 v[178:181], v177 offset:1024
	ds_read_b128 v[182:185], v177 offset:2048
	ds_read_b128 v[186:189], v177 offset:3072
	ds_read_b128 v[190:193], v177 offset:4096
	ds_read_b128 v[208:211], v177 offset:5120
	ds_read_b128 v[212:215], v177 offset:6144
	ds_read_b128 v[216:219], v177 offset:7168
	global_load_lds_dwordx4 v[220:221], off
	v_lshl_add_u64 v[220:221], s[30:31], 0, v[156:157]
	s_add_i32 m0, s29, 0xe000
	s_nop 0
	global_load_lds_dwordx4 v[220:221], off
	s_waitcnt vmcnt(8)
	s_waitcnt lgkmcnt(0)
	s_barrier
	s_waitcnt lgkmcnt(0)
	v_mfma_f32_16x16x32_bf16 v[126:129], v[130:133], v[172:175], v[126:129]
	v_mfma_f32_16x16x32_bf16 v[122:125], v[138:141], v[172:175], v[122:125]
	v_mfma_f32_16x16x32_bf16 v[118:121], v[130:133], v[182:185], v[118:121]
	v_mfma_f32_16x16x32_bf16 v[114:117], v[138:141], v[182:185], v[114:117]
	v_mfma_f32_16x16x32_bf16 v[102:105], v[130:133], v[190:193], v[102:105]
	v_mfma_f32_16x16x32_bf16 v[98:101], v[138:141], v[190:193], v[98:101]
	v_mfma_f32_16x16x32_bf16 v[86:89], v[130:133], v[212:215], v[86:89]
	v_mfma_f32_16x16x32_bf16 v[82:85], v[138:141], v[212:215], v[82:85]
	v_mfma_f32_16x16x32_bf16 v[126:129], v[134:137], v[178:181], v[126:129]
	v_mfma_f32_16x16x32_bf16 v[122:125], v[142:145], v[178:181], v[122:125]
	v_mfma_f32_16x16x32_bf16 v[118:121], v[134:137], v[186:189], v[118:121]
	v_mfma_f32_16x16x32_bf16 v[114:117], v[142:145], v[186:189], v[114:117]
	v_mfma_f32_16x16x32_bf16 v[102:105], v[134:137], v[208:211], v[102:105]
	v_mfma_f32_16x16x32_bf16 v[98:101], v[142:145], v[208:211], v[98:101]
	v_mfma_f32_16x16x32_bf16 v[86:89], v[134:137], v[216:219], v[86:89]
	v_mfma_f32_16x16x32_bf16 v[82:85], v[142:145], v[216:219], v[82:85]
	v_mfma_f32_16x16x32_bf16 v[110:113], v[146:149], v[172:175], v[110:113]
	v_mfma_f32_16x16x32_bf16 v[106:109], v[164:167], v[172:175], v[106:109]
	v_mfma_f32_16x16x32_bf16 v[94:97], v[146:149], v[182:185], v[94:97]
	v_mfma_f32_16x16x32_bf16 v[90:93], v[164:167], v[182:185], v[90:93]
	v_mfma_f32_16x16x32_bf16 v[78:81], v[146:149], v[190:193], v[78:81]
	v_mfma_f32_16x16x32_bf16 v[74:77], v[164:167], v[190:193], v[74:77]
	v_mfma_f32_16x16x32_bf16 v[70:73], v[146:149], v[212:215], v[70:73]
	v_mfma_f32_16x16x32_bf16 v[66:69], v[164:167], v[212:215], v[66:69]
	v_mfma_f32_16x16x32_bf16 v[110:113], v[160:163], v[178:181], v[110:113]
	v_mfma_f32_16x16x32_bf16 v[106:109], v[168:171], v[178:181], v[106:109]
	v_mfma_f32_16x16x32_bf16 v[94:97], v[160:163], v[186:189], v[94:97]
	v_mfma_f32_16x16x32_bf16 v[90:93], v[168:171], v[186:189], v[90:93]
	v_mfma_f32_16x16x32_bf16 v[78:81], v[160:163], v[208:211], v[78:81]
	v_mfma_f32_16x16x32_bf16 v[74:77], v[168:171], v[208:211], v[74:77]
	v_mfma_f32_16x16x32_bf16 v[70:73], v[160:163], v[216:219], v[70:73]
	v_mfma_f32_16x16x32_bf16 v[66:69], v[168:171], v[216:219], v[66:69]
	s_barrier
	s_add_i32 s40, s40, s59
	v_lshl_add_u64 v[220:221], s[34:35], 0, v[0:1]
	s_mov_b32 m0, s40
	ds_read_b128 v[172:175], v177 offset:16384
	ds_read_b128 v[178:181], v177 offset:17408
	ds_read_b128 v[182:185], v177 offset:18432
	ds_read_b128 v[186:189], v177 offset:19456
	ds_read_b128 v[190:193], v177 offset:20480
	ds_read_b128 v[208:211], v177 offset:21504
	ds_read_b128 v[212:215], v177 offset:22528
	ds_read_b128 v[216:219], v177 offset:23552
	global_load_lds_dwordx4 v[220:221], off
	s_add_i32 m0, s40, 0x2000
	s_add_u32 s40, s34, 0x200000
	v_lshl_add_u64 v[222:223], s[34:35], 0, v[154:155]
	s_addc_u32 s41, s35, 0
	s_add_i32 s27, s27, s59
	global_load_lds_dwordx4 v[222:223], off
	v_lshl_add_u64 v[224:225], s[40:41], 0, v[0:1]
	s_mov_b32 m0, s27
	v_lshl_add_u64 v[226:227], s[36:37], 0, v[152:153]
	global_load_lds_dwordx4 v[224:225], off
	v_lshl_add_u64 v[224:225], s[40:41], 0, v[154:155]
	s_add_i32 m0, s27, 0x2000
	s_nop 0
	global_load_lds_dwordx4 v[224:225], off
	v_lshl_add_u64 v[224:225], s[36:37], 0, v[150:151]
	s_mov_b32 m0, s29
	s_nop 0
	global_load_lds_dwordx4 v[224:225], off
	s_mov_b32 m0, s52
	s_nop 0
	global_load_lds_dwordx4 v[226:227], off
	s_waitcnt vmcnt(8)
	s_waitcnt lgkmcnt(0)
	s_barrier
	s_waitcnt lgkmcnt(0)
	v_mfma_f32_16x16x32_bf16 v[62:65], v[130:133], v[172:175], v[62:65]
	v_mfma_f32_16x16x32_bf16 v[58:61], v[138:141], v[172:175], v[58:61]
	v_mfma_f32_16x16x32_bf16 v[54:57], v[130:133], v[182:185], v[54:57]
	v_mfma_f32_16x16x32_bf16 v[50:53], v[138:141], v[182:185], v[50:53]
	v_mfma_f32_16x16x32_bf16 v[38:41], v[130:133], v[190:193], v[38:41]
	v_mfma_f32_16x16x32_bf16 v[34:37], v[138:141], v[190:193], v[34:37]
	v_mfma_f32_16x16x32_bf16 v[22:25], v[130:133], v[212:215], v[22:25]
	v_mfma_f32_16x16x32_bf16 v[18:21], v[138:141], v[212:215], v[18:21]
	v_mfma_f32_16x16x32_bf16 v[62:65], v[134:137], v[178:181], v[62:65]
	v_mfma_f32_16x16x32_bf16 v[58:61], v[142:145], v[178:181], v[58:61]
	v_mfma_f32_16x16x32_bf16 v[54:57], v[134:137], v[186:189], v[54:57]
	v_mfma_f32_16x16x32_bf16 v[50:53], v[142:145], v[186:189], v[50:53]
	v_mfma_f32_16x16x32_bf16 v[38:41], v[134:137], v[208:211], v[38:41]
	v_mfma_f32_16x16x32_bf16 v[34:37], v[142:145], v[208:211], v[34:37]
	v_mfma_f32_16x16x32_bf16 v[22:25], v[134:137], v[216:219], v[22:25]
	v_mfma_f32_16x16x32_bf16 v[18:21], v[142:145], v[216:219], v[18:21]
	v_mfma_f32_16x16x32_bf16 v[46:49], v[146:149], v[172:175], v[46:49]
	v_mfma_f32_16x16x32_bf16 v[42:45], v[164:167], v[172:175], v[42:45]
	v_mfma_f32_16x16x32_bf16 v[30:33], v[146:149], v[182:185], v[30:33]
	v_mfma_f32_16x16x32_bf16 v[26:29], v[164:167], v[182:185], v[26:29]
	v_mfma_f32_16x16x32_bf16 v[14:17], v[146:149], v[190:193], v[14:17]
	v_mfma_f32_16x16x32_bf16 v[10:13], v[164:167], v[190:193], v[10:13]
	v_mfma_f32_16x16x32_bf16 v[6:9], v[146:149], v[212:215], v[6:9]
	v_mfma_f32_16x16x32_bf16 v[2:5], v[164:167], v[212:215], v[2:5]
	v_mfma_f32_16x16x32_bf16 v[46:49], v[160:163], v[178:181], v[46:49]
	v_mfma_f32_16x16x32_bf16 v[42:45], v[168:171], v[178:181], v[42:45]
	v_mfma_f32_16x16x32_bf16 v[30:33], v[160:163], v[186:189], v[30:33]
	v_mfma_f32_16x16x32_bf16 v[26:29], v[168:171], v[186:189], v[26:29]
	v_mfma_f32_16x16x32_bf16 v[14:17], v[160:163], v[208:211], v[14:17]
	v_mfma_f32_16x16x32_bf16 v[10:13], v[168:171], v[208:211], v[10:13]
	v_mfma_f32_16x16x32_bf16 v[6:9], v[160:163], v[216:219], v[6:9]
	v_mfma_f32_16x16x32_bf16 v[2:5], v[168:171], v[216:219], v[2:5]
	s_barrier
; #define PG8_STAGE(bufoff, gbase, voff) do { _Pragma("unroll") for (int _i = 0; _i < 2; ++_i) \
;         __builtin_amdgcn_global_load_lds((const unsigned*)((const char*)(gbase) + (voff)[_i]), (PG8_LAS unsigned*)(lds + (bufoff) + ldsw + _i * 8192), 16, 0, 0); } while (0)
; #define PG8_LDA(dst, b, h) do { _Pragma("unroll") for (int m = 0; m < 4; ++m) _Pragma("unroll") for (int k = 0; k < 2; ++k) dst[m][k] = *(const PG8_LAS bf16x8*)(lds + PG8_SA(b, h) + aoff + m * 2048 + k * 1024); } while (0)
; #define PG8_LDB(dst, b, h) do { _Pragma("unroll") for (int n = 0; n < 2; ++n) _Pragma("unroll") for (int k = 0; k < 2; ++k) dst[n][k] = *(const PG8_LAS bf16x8*)(lds + PG8_SB(b, h) + boff + n * 2048 + k * 1024); } while (0)
; #define PG8_MMA(ai, bj, At, Bt) do { __builtin_amdgcn_s_setprio(1); _Pragma("unroll") for (int m = 0; m < 4; ++m) _Pragma("unroll") for (int n = 0; n < 2; ++n) _Pragma("unroll") for (int k = 0; k < 2; ++k) \
;         acc[ai][bj][m][n] = __builtin_amdgcn_mfma_f32_16x16x32_bf16(Bt[n][k], At[m][k], acc[ai][bj][m][n], 0, 0, 0); __builtin_amdgcn_s_setprio(0); } while (0)
; #define PG8_WAIT_V(n) asm volatile("s_waitcnt vmcnt(" #n ")" ::: "memory")
; #define PG8_WAIT_L(n) asm volatile("s_waitcnt lgkmcnt(" #n ")" ::: "memory")
; #define PG8_BAR __builtin_amdgcn_s_barrier()
; #define PG8_SCHED __builtin_amdgcn_sched_barrier(0)
; template <class Epi, class Sched, bool ALIGN_EPI = false, bool SP2 = false>
; __device__ __forceinline__ void gemm_phase(PG8_LAS unsigned char* lds, const Gemm g, const Sched& S, const Epi& E, int wid_in) {
;     ...
;             PG8_LDB(B0, 1, 0); PG8_LDB(B1, 1, 1); PG8_SCHED; PG8_LDA(At, 1, 0); PG8_STAGE(PG8_SA(0, 1), a2 + hstep, voffA);
;             PG8_WAIT_V(8); PG8_WAIT_L(0); PG8_BAR; PG8_MMA(0, 0, At, B0); PG8_MMA(0, 1, At, B1); PG8_BAR; PG8_SCHED;
	s_add_i32 s27, 0, 0x18000
	s_add_i32 s40, 0, 0x1c000
	v_add_u32_e32 v142, s27, v176
	v_add_u32_e32 v168, s40, v176
	ds_read_b128 v[130:133], v142
	ds_read_b128 v[134:137], v142 offset:1024
	ds_read_b128 v[138:141], v142 offset:2048
	ds_read_b128 v[142:145], v142 offset:3072
	ds_read_b128 v[146:149], v168
	ds_read_b128 v[160:163], v168 offset:1024
	ds_read_b128 v[164:167], v168 offset:2048
	ds_read_b128 v[168:171], v168 offset:3072
	s_add_u32 s36, s36, 0x200000
	s_addc_u32 s37, s37, 0
	s_mov_b32 m0, s53
	v_lshl_add_u64 v[228:229], s[36:37], 0, v[150:151]
	ds_read_b128 v[172:175], v177 offset:32768
	ds_read_b128 v[178:181], v177 offset:33792
	ds_read_b128 v[182:185], v177 offset:34816
	ds_read_b128 v[186:189], v177 offset:35840
	ds_read_b128 v[190:193], v177 offset:36864
	ds_read_b128 v[208:211], v177 offset:37888
	ds_read_b128 v[212:215], v177 offset:38912
	ds_read_b128 v[216:219], v177 offset:39936
	global_load_lds_dwordx4 v[228:229], off
	v_lshl_add_u64 v[228:229], s[36:37], 0, v[152:153]
	s_mov_b32 m0, s61
	s_nop 0
	global_load_lds_dwordx4 v[228:229], off
	s_waitcnt vmcnt(8)
	s_waitcnt lgkmcnt(0)
	s_barrier
	s_waitcnt lgkmcnt(0)
	v_mfma_f32_16x16x32_bf16 v[126:129], v[130:133], v[172:175], v[126:129]
	v_mfma_f32_16x16x32_bf16 v[122:125], v[138:141], v[172:175], v[122:125]
	v_mfma_f32_16x16x32_bf16 v[118:121], v[130:133], v[182:185], v[118:121]
	v_mfma_f32_16x16x32_bf16 v[114:117], v[138:141], v[182:185], v[114:117]
	v_mfma_f32_16x16x32_bf16 v[102:105], v[130:133], v[190:193], v[102:105]
	v_mfma_f32_16x16x32_bf16 v[98:101], v[138:141], v[190:193], v[98:101]
	v_mfma_f32_16x16x32_bf16 v[86:89], v[130:133], v[212:215], v[86:89]
	v_mfma_f32_16x16x32_bf16 v[82:85], v[138:141], v[212:215], v[82:85]
	v_mfma_f32_16x16x32_bf16 v[126:129], v[134:137], v[178:181], v[126:129]
	v_mfma_f32_16x16x32_bf16 v[122:125], v[142:145], v[178:181], v[122:125]
	v_mfma_f32_16x16x32_bf16 v[118:121], v[134:137], v[186:189], v[118:121]
	v_mfma_f32_16x16x32_bf16 v[114:117], v[142:145], v[186:189], v[114:117]
	v_mfma_f32_16x16x32_bf16 v[102:105], v[134:137], v[208:211], v[102:105]
	v_mfma_f32_16x16x32_bf16 v[98:101], v[142:145], v[208:211], v[98:101]
	v_mfma_f32_16x16x32_bf16 v[86:89], v[134:137], v[216:219], v[86:89]
	v_mfma_f32_16x16x32_bf16 v[82:85], v[142:145], v[216:219], v[82:85]
	v_mfma_f32_16x16x32_bf16 v[110:113], v[146:149], v[172:175], v[110:113]
	v_mfma_f32_16x16x32_bf16 v[106:109], v[164:167], v[172:175], v[106:109]
	v_mfma_f32_16x16x32_bf16 v[94:97], v[146:149], v[182:185], v[94:97]
	v_mfma_f32_16x16x32_bf16 v[90:93], v[164:167], v[182:185], v[90:93]
	v_mfma_f32_16x16x32_bf16 v[78:81], v[146:149], v[190:193], v[78:81]
	v_mfma_f32_16x16x32_bf16 v[74:77], v[164:167], v[190:193], v[74:77]
	v_mfma_f32_16x16x32_bf16 v[70:73], v[146:149], v[212:215], v[70:73]
	v_mfma_f32_16x16x32_bf16 v[66:69], v[164:167], v[212:215], v[66:69]
	v_mfma_f32_16x16x32_bf16 v[110:113], v[160:163], v[178:181], v[110:113]
	v_mfma_f32_16x16x32_bf16 v[106:109], v[168:171], v[178:181], v[106:109]
	v_mfma_f32_16x16x32_bf16 v[94:97], v[160:163], v[186:189], v[94:97]
	v_mfma_f32_16x16x32_bf16 v[90:93], v[168:171], v[186:189], v[90:93]
	v_mfma_f32_16x16x32_bf16 v[78:81], v[160:163], v[208:211], v[78:81]
	v_mfma_f32_16x16x32_bf16 v[74:77], v[168:171], v[208:211], v[74:77]
	v_mfma_f32_16x16x32_bf16 v[70:73], v[160:163], v[216:219], v[70:73]
	v_mfma_f32_16x16x32_bf16 v[66:69], v[168:171], v[216:219], v[66:69]
	s_barrier
; #define PG8_STAGE(bufoff, gbase, voff) do { _Pragma("unroll") for (int _i = 0; _i < 2; ++_i) \
;         __builtin_amdgcn_global_load_lds((const unsigned*)((const char*)(gbase) + (voff)[_i]), (PG8_LAS unsigned*)(lds + (bufoff) + ldsw + _i * 8192), 16, 0, 0); } while (0)
; #define PG8_LDA(dst, b, h) do { _Pragma("unroll") for (int m = 0; m < 4; ++m) _Pragma("unroll") for (int k = 0; k < 2; ++k) dst[m][k] = *(const PG8_LAS bf16x8*)(lds + PG8_SA(b, h) + aoff + m * 2048 + k * 1024); } while (0)
; #define PG8_MMA(ai, bj, At, Bt) do { __builtin_amdgcn_s_setprio(1); _Pragma("unroll") for (int m = 0; m < 4; ++m) _Pragma("unroll") for (int n = 0; n < 2; ++n) _Pragma("unroll") for (int k = 0; k < 2; ++k) \
;         acc[ai][bj][m][n] = __builtin_amdgcn_mfma_f32_16x16x32_bf16(Bt[n][k], At[m][k], acc[ai][bj][m][n], 0, 0, 0); __builtin_amdgcn_s_setprio(0); } while (0)
; #define PG8_WAIT_V(n) asm volatile("s_waitcnt vmcnt(" #n ")" ::: "memory")
; #define PG8_WAIT_L(n) asm volatile("s_waitcnt lgkmcnt(" #n ")" ::: "memory")
; #define PG8_BAR __builtin_amdgcn_s_barrier()
; #define PG8_SCHED __builtin_amdgcn_sched_barrier(0)
; template <class Epi, class Sched, bool ALIGN_EPI = false, bool SP2 = false>
; __device__ __forceinline__ void gemm_phase(PG8_LAS unsigned char* lds, const Gemm g, const Sched& S, const Epi& E, int wid_in) {
;     ...
;         for (int t = 0; t < nt; t += 2) {
;             const bool last = (t == nt - 2);
;             const char* a1 = cA + (size_t)(t + 1) * kstep;
;             const char* a2 = last ? nA : cA + (size_t)(t + 2) * kstep; const char* b2 = last ? nB : cB + (size_t)(t + 2) * kstep;
;             const char* a3 = a2 + kstep; const char* b3 = b2 + kstep;
;     ...
;             PG8_LDA(At, 1, 1); PG8_STAGE(PG8_SB(1, 0), b3, voffB); PG8_STAGE(PG8_SB(1, 1), b3 + hstep, voffB); PG8_STAGE(PG8_SA(1, 0), a3, voffA);
;             PG8_WAIT_V(8); PG8_WAIT_L(0); PG8_BAR; PG8_MMA(1, 0, At, B0); PG8_MMA(1, 1, At, B1); PG8_BAR; PG8_SCHED;
	s_add_i32 s27, s27, s59
	v_lshl_add_u64 v[220:221], v[220:221], 0, s[94:95]
	s_mov_b32 m0, s27
	ds_read_b128 v[172:175], v177 offset:49152
	ds_read_b128 v[178:181], v177 offset:50176
	ds_read_b128 v[182:185], v177 offset:51200
	ds_read_b128 v[186:189], v177 offset:52224
	ds_read_b128 v[190:193], v177 offset:53248
	ds_read_b128 v[208:211], v177 offset:54272
	ds_read_b128 v[212:215], v177 offset:55296
	ds_read_b128 v[216:219], v177 offset:56320
	global_load_lds_dwordx4 v[220:221], off
	s_add_i32 m0, s27, 0x2000
	s_add_u32 s34, s34, 0x200080
	v_lshl_add_u64 v[220:221], v[222:223], 0, s[94:95]
	s_addc_u32 s35, s35, 0
	s_add_i32 s27, s40, s59
	global_load_lds_dwordx4 v[220:221], off
	v_lshl_add_u64 v[220:221], s[34:35], 0, v[0:1]
	s_mov_b32 m0, s27
	s_nop 0
	global_load_lds_dwordx4 v[220:221], off
	v_lshl_add_u64 v[220:221], s[34:35], 0, v[154:155]
	s_add_i32 m0, s27, 0x2000
	s_nop 0
	global_load_lds_dwordx4 v[220:221], off
	v_lshl_add_u64 v[220:221], v[224:225], 0, s[94:95]
	s_mov_b32 m0, s73
	s_nop 0
	global_load_lds_dwordx4 v[220:221], off
	v_lshl_add_u64 v[220:221], v[226:227], 0, s[94:95]
	s_mov_b32 m0, s80
	s_nop 0
	global_load_lds_dwordx4 v[220:221], off
	s_waitcnt vmcnt(8)
	s_waitcnt lgkmcnt(0)
	s_barrier
	s_waitcnt lgkmcnt(0)
	v_mfma_f32_16x16x32_bf16 v[62:65], v[130:133], v[172:175], v[62:65]
	v_mfma_f32_16x16x32_bf16 v[58:61], v[138:141], v[172:175], v[58:61]
	v_mfma_f32_16x16x32_bf16 v[54:57], v[130:133], v[182:185], v[54:57]
	v_mfma_f32_16x16x32_bf16 v[50:53], v[138:141], v[182:185], v[50:53]
	v_mfma_f32_16x16x32_bf16 v[38:41], v[130:133], v[190:193], v[38:41]
	v_mfma_f32_16x16x32_bf16 v[34:37], v[138:141], v[190:193], v[34:37]
	v_mfma_f32_16x16x32_bf16 v[22:25], v[130:133], v[212:215], v[22:25]
	v_mfma_f32_16x16x32_bf16 v[18:21], v[138:141], v[212:215], v[18:21]
	v_mfma_f32_16x16x32_bf16 v[62:65], v[134:137], v[178:181], v[62:65]
	v_mfma_f32_16x16x32_bf16 v[58:61], v[142:145], v[178:181], v[58:61]
	v_mfma_f32_16x16x32_bf16 v[54:57], v[134:137], v[186:189], v[54:57]
	v_mfma_f32_16x16x32_bf16 v[50:53], v[142:145], v[186:189], v[50:53]
	v_mfma_f32_16x16x32_bf16 v[38:41], v[134:137], v[208:211], v[38:41]
	v_mfma_f32_16x16x32_bf16 v[34:37], v[142:145], v[208:211], v[34:37]
	v_mfma_f32_16x16x32_bf16 v[22:25], v[134:137], v[216:219], v[22:25]
	v_mfma_f32_16x16x32_bf16 v[18:21], v[142:145], v[216:219], v[18:21]
	v_mfma_f32_16x16x32_bf16 v[46:49], v[146:149], v[172:175], v[46:49]
	v_mfma_f32_16x16x32_bf16 v[42:45], v[164:167], v[172:175], v[42:45]
	v_mfma_f32_16x16x32_bf16 v[30:33], v[146:149], v[182:185], v[30:33]
	v_mfma_f32_16x16x32_bf16 v[26:29], v[164:167], v[182:185], v[26:29]
	v_mfma_f32_16x16x32_bf16 v[14:17], v[146:149], v[190:193], v[14:17]
	v_mfma_f32_16x16x32_bf16 v[10:13], v[164:167], v[190:193], v[10:13]
	v_mfma_f32_16x16x32_bf16 v[6:9], v[146:149], v[212:215], v[6:9]
	v_mfma_f32_16x16x32_bf16 v[2:5], v[164:167], v[212:215], v[2:5]
	v_mfma_f32_16x16x32_bf16 v[46:49], v[160:163], v[178:181], v[46:49]
	v_mfma_f32_16x16x32_bf16 v[42:45], v[168:171], v[178:181], v[42:45]
	v_mfma_f32_16x16x32_bf16 v[30:33], v[160:163], v[186:189], v[30:33]
	v_mfma_f32_16x16x32_bf16 v[26:29], v[168:171], v[186:189], v[26:29]
	v_mfma_f32_16x16x32_bf16 v[14:17], v[160:163], v[208:211], v[14:17]
	v_mfma_f32_16x16x32_bf16 v[10:13], v[168:171], v[208:211], v[10:13]
	v_mfma_f32_16x16x32_bf16 v[6:9], v[160:163], v[216:219], v[6:9]
	v_mfma_f32_16x16x32_bf16 v[2:5], v[168:171], v[216:219], v[2:5]
	s_add_u32 s19, s19, 0x100
	s_addc_u32 s21, s21, 0
	s_add_u32 s30, s30, 0x100
	s_addc_u32 s31, s31, 0
	s_cmp_ge_i32 s56, s90
	s_mov_b32 s27, s56
	s_cbranch_scc1 .Lrot_exit_5
	s_add_i32 s56, s27, 2
	s_add_u32 s34, s30, 0xffe00080
	s_addc_u32 s35, s31, -1
	s_add_i32 s40, 0, 0x10000
	s_cmp_eq_u32 s17, s27
	s_cselect_b32 s37, s23, s35
	s_cselect_b32 s36, s22, s34
	s_cselect_b32 s35, s25, s21
	s_cselect_b32 s34, s24, s19
	s_add_i32 s27, 0, 0x14000
	v_add_u32_e32 v142, s40, v176
	v_add_u32_e32 v168, s27, v176
	s_barrier
	s_branch .Lrot_5
